# v93 + non-temporal (nt) stores in the hand-written G1 epilogue (K/V/Q/gate outputs streamed past L2 retention)
# speedup vs baseline: 1.0101x; 1.0062x over previous
; #define LAS __attribute__((address_space(3)))
; #define GAS __attribute__((address_space(1)))
; __host__ __device__ __forceinline__ size_t bl512(size_t row, int col) { return ((row >> 5) * 64 + (size_t)(col >> 3)) * 256 + (row & 31) * 8 + (col & 7); }
;     __device__ __forceinline__ void operator()(const f32x4 (&acc)[2][2][4][2], const Unit& u, int wr, int wc, int fr, int fq) const {
;     ...
;         const int slot = (tags[0] == u.pm) ? 0 : (tags[1] == u.pm) ? 1 : -1;
;         const LAS float* rtab = (const LAS float*)rsc + (slot > 0 ? 256 : 0) + wr * 64 + fr;
; #pragma unroll
;         for (int ai = 0; ai < 2; ++ai)
; #pragma unroll
;             for (int m = 0; m < 4; ++m) {
;                 const int row = row0 + ai * HALF + m * 16;
;                 float rs;
;                 if (slot >= 0) rs = rtab[ai * HALF + m * 16];
;                 else {
;                     const f32x4 pv = *(const GAS f32x4*)(part + (size_t)row * 16 + fq * 4);
;                     float s = (pv[0] + pv[1]) + (pv[2] + pv[3]);
;                     s = row4_sum(s);
;                     rs = __builtin_amdgcn_rsqf(s * (1.0f / DM) + RMS_EPS);
;                 }
;                 f32x4 v[2][2];
; #pragma unroll
;                 for (int bj = 0; bj < 2; ++bj)
; #pragma unroll
;                     for (int n = 0; n < 2; ++n) v[bj][n] = acc[ai][bj][m][n] * rs;
;     ...
;                 GAS f16* rowp = isqg ? QG + (size_t)dsec * QG_SEC + bl512((size_t)row, cs) : KV + (size_t)row * KVW + dsec * 512 + cs;
; #pragma unroll
;                 for (int bj = 0; bj < 2; ++bj) {
;                     u32x4 w; w.x = pkh(v[bj][0][0], v[bj][0][1]); w.y = pkh(v[bj][0][2], v[bj][0][3]); w.z = pkh(v[bj][1][0], v[bj][1][1]); w.w = pkh(v[bj][1][2], v[bj][1][3]);
;                     *(GAS u32x4*)(rowp + bjstep * bj) = w;
;                 }
.Lepi_kvp:
	s_and_b32 s0, s70, 1
	s_lshl_b32 s0, s0, 10
	v_add_u32_e32 v132, s0, v219
	ds_read_b32 v134, v132
	ds_read_b32 v136, v132 offset:64
	ds_read_b32 v138, v132 offset:128
	ds_read_b32 v140, v132 offset:192
	ds_read_b32 v142, v132 offset:512
	ds_read_b32 v144, v132 offset:576
	ds_read_b32 v146, v132 offset:640
	ds_read_b32 v148, v132 offset:704
	s_lshr_b32 s0, s69, 2
	s_and_b32 s1, s69, 1
	v_lshl_add_u32 v133, s68, 8, v187
	v_lshlrev_b32_e32 v133, 12, v133
	v_lshl_add_u32 v133, v220, 1, v133
	s_lshl_b32 s0, s0, 10
	s_lshl_b32 s1, s1, 9
	s_add_u32 s0, s0, s1
	s_add_u32 s4, s8, s0
	s_addc_u32 s5, s9, 0
	s_waitcnt lgkmcnt(0)
	s_mov_b32 s6, s4
	s_mov_b32 s7, s5
	v_pk_mul_f32 v[128:129], v[128:129], v[134:135] op_sel_hi:[1,0]
	v_pk_mul_f32 v[130:131], v[130:131], v[134:135] op_sel_hi:[1,0]
	v_pk_mul_f32 v[124:125], v[124:125], v[134:135] op_sel_hi:[1,0]
	v_pk_mul_f32 v[126:127], v[126:127], v[134:135] op_sel_hi:[1,0]
	v_pk_mul_f32 v[96:97], v[96:97], v[134:135] op_sel_hi:[1,0]
	v_pk_mul_f32 v[98:99], v[98:99], v[134:135] op_sel_hi:[1,0]
	v_pk_mul_f32 v[92:93], v[92:93], v[134:135] op_sel_hi:[1,0]
	v_pk_mul_f32 v[94:95], v[94:95], v[134:135] op_sel_hi:[1,0]
	v_cvt_pk_f16_f32 v152, v128, v129
	v_cvt_pk_f16_f32 v153, v130, v131
	v_cvt_pk_f16_f32 v154, v124, v125
	v_cvt_pk_f16_f32 v155, v126, v127
	global_store_dwordx4 v133, v[152:155], s[6:7] nt
	v_cvt_pk_f16_f32 v156, v96, v97
	v_cvt_pk_f16_f32 v157, v98, v99
	v_cvt_pk_f16_f32 v158, v92, v93
	v_cvt_pk_f16_f32 v159, v94, v95
	global_store_dwordx4 v133, v[156:159], s[6:7] offset:64 nt
	s_add_u32 s6, s4, 0x10000
	s_addc_u32 s7, s5, 0
	v_pk_mul_f32 v[120:121], v[120:121], v[136:137] op_sel_hi:[1,0]
	v_pk_mul_f32 v[122:123], v[122:123], v[136:137] op_sel_hi:[1,0]
	v_pk_mul_f32 v[116:117], v[116:117], v[136:137] op_sel_hi:[1,0]
	v_pk_mul_f32 v[118:119], v[118:119], v[136:137] op_sel_hi:[1,0]
	v_pk_mul_f32 v[88:89], v[88:89], v[136:137] op_sel_hi:[1,0]
	v_pk_mul_f32 v[90:91], v[90:91], v[136:137] op_sel_hi:[1,0]
	v_pk_mul_f32 v[84:85], v[84:85], v[136:137] op_sel_hi:[1,0]
	v_pk_mul_f32 v[86:87], v[86:87], v[136:137] op_sel_hi:[1,0]
	v_cvt_pk_f16_f32 v160, v120, v121
	v_cvt_pk_f16_f32 v161, v122, v123
	v_cvt_pk_f16_f32 v162, v116, v117
	v_cvt_pk_f16_f32 v163, v118, v119
	global_store_dwordx4 v133, v[160:163], s[6:7] nt
	v_cvt_pk_f16_f32 v164, v88, v89
	v_cvt_pk_f16_f32 v165, v90, v91
	v_cvt_pk_f16_f32 v166, v84, v85
	v_cvt_pk_f16_f32 v167, v86, v87
	global_store_dwordx4 v133, v[164:167], s[6:7] offset:64 nt
	s_add_u32 s6, s4, 0x20000
	s_addc_u32 s7, s5, 0
	v_pk_mul_f32 v[112:113], v[112:113], v[138:139] op_sel_hi:[1,0]
	v_pk_mul_f32 v[114:115], v[114:115], v[138:139] op_sel_hi:[1,0]
	v_pk_mul_f32 v[108:109], v[108:109], v[138:139] op_sel_hi:[1,0]
	v_pk_mul_f32 v[110:111], v[110:111], v[138:139] op_sel_hi:[1,0]
	v_pk_mul_f32 v[80:81], v[80:81], v[138:139] op_sel_hi:[1,0]
	v_pk_mul_f32 v[82:83], v[82:83], v[138:139] op_sel_hi:[1,0]
	v_pk_mul_f32 v[76:77], v[76:77], v[138:139] op_sel_hi:[1,0]
	v_pk_mul_f32 v[78:79], v[78:79], v[138:139] op_sel_hi:[1,0]
	v_cvt_pk_f16_f32 v152, v112, v113
	v_cvt_pk_f16_f32 v153, v114, v115
	v_cvt_pk_f16_f32 v154, v108, v109
	v_cvt_pk_f16_f32 v155, v110, v111
	global_store_dwordx4 v133, v[152:155], s[6:7] nt
	v_cvt_pk_f16_f32 v156, v80, v81
	v_cvt_pk_f16_f32 v157, v82, v83
	v_cvt_pk_f16_f32 v158, v76, v77
	v_cvt_pk_f16_f32 v159, v78, v79
	global_store_dwordx4 v133, v[156:159], s[6:7] offset:64 nt
	s_add_u32 s6, s4, 0x30000
	s_addc_u32 s7, s5, 0
	v_pk_mul_f32 v[104:105], v[104:105], v[140:141] op_sel_hi:[1,0]
	v_pk_mul_f32 v[106:107], v[106:107], v[140:141] op_sel_hi:[1,0]
	v_pk_mul_f32 v[100:101], v[100:101], v[140:141] op_sel_hi:[1,0]
	v_pk_mul_f32 v[102:103], v[102:103], v[140:141] op_sel_hi:[1,0]
	v_pk_mul_f32 v[72:73], v[72:73], v[140:141] op_sel_hi:[1,0]
	v_pk_mul_f32 v[74:75], v[74:75], v[140:141] op_sel_hi:[1,0]
	v_pk_mul_f32 v[68:69], v[68:69], v[140:141] op_sel_hi:[1,0]
	v_pk_mul_f32 v[70:71], v[70:71], v[140:141] op_sel_hi:[1,0]
	v_cvt_pk_f16_f32 v160, v104, v105
	v_cvt_pk_f16_f32 v161, v106, v107
	v_cvt_pk_f16_f32 v162, v100, v101
	v_cvt_pk_f16_f32 v163, v102, v103
	global_store_dwordx4 v133, v[160:163], s[6:7] nt
	v_cvt_pk_f16_f32 v164, v72, v73
	v_cvt_pk_f16_f32 v165, v74, v75
	v_cvt_pk_f16_f32 v166, v68, v69
	v_cvt_pk_f16_f32 v167, v70, v71
	global_store_dwordx4 v133, v[164:167], s[6:7] offset:64 nt
	s_add_u32 s6, s4, 0x80000
	s_addc_u32 s7, s5, 0
	v_pk_mul_f32 v[64:65], v[64:65], v[142:143] op_sel_hi:[1,0]
	v_pk_mul_f32 v[66:67], v[66:67], v[142:143] op_sel_hi:[1,0]
	v_pk_mul_f32 v[60:61], v[60:61], v[142:143] op_sel_hi:[1,0]
	v_pk_mul_f32 v[62:63], v[62:63], v[142:143] op_sel_hi:[1,0]
	v_pk_mul_f32 v[32:33], v[32:33], v[142:143] op_sel_hi:[1,0]
	v_pk_mul_f32 v[34:35], v[34:35], v[142:143] op_sel_hi:[1,0]
	v_pk_mul_f32 v[28:29], v[28:29], v[142:143] op_sel_hi:[1,0]
	v_pk_mul_f32 v[30:31], v[30:31], v[142:143] op_sel_hi:[1,0]
	v_cvt_pk_f16_f32 v152, v64, v65
	v_cvt_pk_f16_f32 v153, v66, v67
	v_cvt_pk_f16_f32 v154, v60, v61
	v_cvt_pk_f16_f32 v155, v62, v63
	global_store_dwordx4 v133, v[152:155], s[6:7] nt
	v_cvt_pk_f16_f32 v156, v32, v33
	v_cvt_pk_f16_f32 v157, v34, v35
	v_cvt_pk_f16_f32 v158, v28, v29
	v_cvt_pk_f16_f32 v159, v30, v31
	global_store_dwordx4 v133, v[156:159], s[6:7] offset:64 nt
	s_add_u32 s6, s4, 0x90000
	s_addc_u32 s7, s5, 0
	v_pk_mul_f32 v[56:57], v[56:57], v[144:145] op_sel_hi:[1,0]
	v_pk_mul_f32 v[58:59], v[58:59], v[144:145] op_sel_hi:[1,0]
	v_pk_mul_f32 v[52:53], v[52:53], v[144:145] op_sel_hi:[1,0]
	v_pk_mul_f32 v[54:55], v[54:55], v[144:145] op_sel_hi:[1,0]
	v_pk_mul_f32 v[24:25], v[24:25], v[144:145] op_sel_hi:[1,0]
; #define GAS __attribute__((address_space(1)))
;     __device__ __forceinline__ void operator()(const f32x4 (&acc)[2][2][4][2], const Unit& u, int wr, int wc, int fr, int fq) const {
;     ...
;                 const int row = row0 + ai * HALF + m * 16;
;                 float rs;
;                 if (slot >= 0) rs = rtab[ai * HALF + m * 16];
;                 else {
;                     const f32x4 pv = *(const GAS f32x4*)(part + (size_t)row * 16 + fq * 4);
;                     float s = (pv[0] + pv[1]) + (pv[2] + pv[3]);
;                     s = row4_sum(s);
;                     rs = __builtin_amdgcn_rsqf(s * (1.0f / DM) + RMS_EPS);
;                 }
;                 f32x4 v[2][2];
; #pragma unroll
;                 for (int bj = 0; bj < 2; ++bj)
; #pragma unroll
;                     for (int n = 0; n < 2; ++n) v[bj][n] = acc[ai][bj][m][n] * rs;
;                 if (sec == 4 || sec == 5) {
;                     float ss = 0.f;
; #pragma unroll
;                     for (int bj = 0; bj < 2; ++bj)
; #pragma unroll
;                         for (int n = 0; n < 2; ++n) { const f32x4 x = v[bj][n]; ss += (x[0] * x[0] + x[1] * x[1]) + (x[2] * x[2] + x[3] * x[3]); }
;                     ss = row4_sum(ss);
;                     float rn = __builtin_amdgcn_rsqf(ss * (1.0f / 64.0f) + RMS_EPS);
;                     if (sec == 4) rn *= QS;
; #pragma unroll
;                     for (int bj = 0; bj < 2; ++bj)
; #pragma unroll
;                         for (int n = 0; n < 2; ++n) v[bj][n] = v[bj][n] * rn * gain[bj][n];
;                 } else if (sec == 0) {
; #pragma unroll
;                     for (int bj = 0; bj < 2; ++bj)
; #pragma unroll
;                         for (int n = 0; n < 2; ++n) v[bj][n] = v[bj][n] * QS;
;                 } else if (sec == 3 || sec == 7) {
; #pragma unroll
;                     for (int bj = 0; bj < 2; ++bj)
; #pragma unroll
;                         for (int n = 0; n < 2; ++n)
; #pragma unroll
;                             for (int e = 0; e < 4; ++e) v[bj][n][e] = silu_f(v[bj][n][e]);
;                 }
;                 GAS f16* rowp = isqg ? QG + (size_t)dsec * QG_SEC + bl512((size_t)row, cs) : KV + (size_t)row * KVW + dsec * 512 + cs;
; #pragma unroll
;                 for (int bj = 0; bj < 2; ++bj) {
	v_pk_mul_f32 v[26:27], v[26:27], v[144:145] op_sel_hi:[1,0]
	v_pk_mul_f32 v[20:21], v[20:21], v[144:145] op_sel_hi:[1,0]
	v_pk_mul_f32 v[22:23], v[22:23], v[144:145] op_sel_hi:[1,0]
	v_cvt_pk_f16_f32 v160, v56, v57
	v_cvt_pk_f16_f32 v161, v58, v59
	v_cvt_pk_f16_f32 v162, v52, v53
	v_cvt_pk_f16_f32 v163, v54, v55
	global_store_dwordx4 v133, v[160:163], s[6:7] nt
	v_cvt_pk_f16_f32 v164, v24, v25
	v_cvt_pk_f16_f32 v165, v26, v27
	v_cvt_pk_f16_f32 v166, v20, v21
	v_cvt_pk_f16_f32 v167, v22, v23
	global_store_dwordx4 v133, v[164:167], s[6:7] offset:64 nt
	s_add_u32 s6, s4, 0xa0000
	s_addc_u32 s7, s5, 0
	v_pk_mul_f32 v[48:49], v[48:49], v[146:147] op_sel_hi:[1,0]
	v_pk_mul_f32 v[50:51], v[50:51], v[146:147] op_sel_hi:[1,0]
	v_pk_mul_f32 v[44:45], v[44:45], v[146:147] op_sel_hi:[1,0]
	v_pk_mul_f32 v[46:47], v[46:47], v[146:147] op_sel_hi:[1,0]
	v_pk_mul_f32 v[16:17], v[16:17], v[146:147] op_sel_hi:[1,0]
	v_pk_mul_f32 v[18:19], v[18:19], v[146:147] op_sel_hi:[1,0]
	v_pk_mul_f32 v[12:13], v[12:13], v[146:147] op_sel_hi:[1,0]
	v_pk_mul_f32 v[14:15], v[14:15], v[146:147] op_sel_hi:[1,0]
	v_cvt_pk_f16_f32 v152, v48, v49
	v_cvt_pk_f16_f32 v153, v50, v51
	v_cvt_pk_f16_f32 v154, v44, v45
	v_cvt_pk_f16_f32 v155, v46, v47
	global_store_dwordx4 v133, v[152:155], s[6:7] nt
	v_cvt_pk_f16_f32 v156, v16, v17
	v_cvt_pk_f16_f32 v157, v18, v19
	v_cvt_pk_f16_f32 v158, v12, v13
	v_cvt_pk_f16_f32 v159, v14, v15
	global_store_dwordx4 v133, v[156:159], s[6:7] offset:64 nt
	s_add_u32 s6, s4, 0xb0000
	s_addc_u32 s7, s5, 0
	v_pk_mul_f32 v[40:41], v[40:41], v[148:149] op_sel_hi:[1,0]
	v_pk_mul_f32 v[42:43], v[42:43], v[148:149] op_sel_hi:[1,0]
	v_pk_mul_f32 v[36:37], v[36:37], v[148:149] op_sel_hi:[1,0]
	v_pk_mul_f32 v[38:39], v[38:39], v[148:149] op_sel_hi:[1,0]
	v_pk_mul_f32 v[8:9], v[8:9], v[148:149] op_sel_hi:[1,0]
	v_pk_mul_f32 v[10:11], v[10:11], v[148:149] op_sel_hi:[1,0]
	v_pk_mul_f32 v[4:5], v[4:5], v[148:149] op_sel_hi:[1,0]
	v_pk_mul_f32 v[6:7], v[6:7], v[148:149] op_sel_hi:[1,0]
	v_cvt_pk_f16_f32 v160, v40, v41
	v_cvt_pk_f16_f32 v161, v42, v43
	v_cvt_pk_f16_f32 v162, v36, v37
	v_cvt_pk_f16_f32 v163, v38, v39
	global_store_dwordx4 v133, v[160:163], s[6:7] nt
	v_cvt_pk_f16_f32 v164, v8, v9
	v_cvt_pk_f16_f32 v165, v10, v11
	v_cvt_pk_f16_f32 v166, v4, v5
	v_cvt_pk_f16_f32 v167, v6, v7
	global_store_dwordx4 v133, v[164:167], s[6:7] offset:64 nt
	s_branch .Lepi_done_g1
.Lepi_qs:
	s_and_b32 s0, s70, 1
	s_lshl_b32 s0, s0, 10
	v_add_u32_e32 v132, s0, v219
	ds_read_b32 v134, v132
	ds_read_b32 v136, v132 offset:64
	ds_read_b32 v138, v132 offset:128
	ds_read_b32 v140, v132 offset:192
	ds_read_b32 v142, v132 offset:512
	ds_read_b32 v144, v132 offset:576
	ds_read_b32 v146, v132 offset:640
	ds_read_b32 v148, v132 offset:704
	s_lshr_b32 s0, s69, 2
	s_and_b32 s1, s69, 1
	v_lshrrev_b32_e32 v2, 6, v187
	v_lshrrev_b32_e32 v133, 3, v220
	v_lshl_add_u32 v133, v2, 7, v133
	v_and_b32_e32 v2, 15, v187
	v_lshlrev_b32_e32 v133, 8, v133
	v_lshl_add_u32 v133, v2, 3, v133
	v_lshlrev_b32_e32 v133, 1, v133
	s_lshl_b32 s0, s0, 25
	s_lshl_b32 s1, s1, 14
	s_add_u32 s0, s0, s1
	s_lshl_b32 s1, s68, 18
	s_add_u32 s0, s0, s1
	s_add_u32 s4, s82, s0
	s_addc_u32 s5, s83, 0
	s_waitcnt lgkmcnt(0)
	s_mov_b32 s6, s4
	s_mov_b32 s7, s5
	v_pk_mul_f32 v[128:129], v[128:129], v[134:135] op_sel_hi:[1,0]
	v_pk_mul_f32 v[130:131], v[130:131], v[134:135] op_sel_hi:[1,0]
	v_pk_mul_f32 v[124:125], v[124:125], v[134:135] op_sel_hi:[1,0]
	v_pk_mul_f32 v[126:127], v[126:127], v[134:135] op_sel_hi:[1,0]
	v_pk_mul_f32 v[96:97], v[96:97], v[134:135] op_sel_hi:[1,0]
	v_pk_mul_f32 v[98:99], v[98:99], v[134:135] op_sel_hi:[1,0]
	v_pk_mul_f32 v[92:93], v[92:93], v[134:135] op_sel_hi:[1,0]
	v_pk_mul_f32 v[94:95], v[94:95], v[134:135] op_sel_hi:[1,0]
	v_pk_mul_f32 v[128:129], v[128:129], s[78:79] op_sel_hi:[1,0]
	v_pk_mul_f32 v[130:131], v[130:131], s[78:79] op_sel_hi:[1,0]
	v_pk_mul_f32 v[124:125], v[124:125], s[78:79] op_sel_hi:[1,0]
	v_pk_mul_f32 v[126:127], v[126:127], s[78:79] op_sel_hi:[1,0]
	v_pk_mul_f32 v[96:97], v[96:97], s[78:79] op_sel_hi:[1,0]
	v_pk_mul_f32 v[98:99], v[98:99], s[78:79] op_sel_hi:[1,0]
	v_pk_mul_f32 v[92:93], v[92:93], s[78:79] op_sel_hi:[1,0]
	v_pk_mul_f32 v[94:95], v[94:95], s[78:79] op_sel_hi:[1,0]
	v_cvt_pk_f16_f32 v152, v128, v129
	v_cvt_pk_f16_f32 v153, v130, v131
	v_cvt_pk_f16_f32 v154, v124, v125
	v_cvt_pk_f16_f32 v155, v126, v127
	global_store_dwordx4 v133, v[152:155], s[6:7] nt
	v_cvt_pk_f16_f32 v156, v96, v97
	v_cvt_pk_f16_f32 v157, v98, v99
	v_cvt_pk_f16_f32 v158, v92, v93
	v_cvt_pk_f16_f32 v159, v94, v95
	global_store_dwordx4 v133, v[156:159], s[6:7] offset:2048 nt
	s_add_u32 s6, s4, 0x100
	s_addc_u32 s7, s5, 0
	v_pk_mul_f32 v[120:121], v[120:121], v[136:137] op_sel_hi:[1,0]
	v_pk_mul_f32 v[122:123], v[122:123], v[136:137] op_sel_hi:[1,0]
	v_pk_mul_f32 v[116:117], v[116:117], v[136:137] op_sel_hi:[1,0]
	v_pk_mul_f32 v[118:119], v[118:119], v[136:137] op_sel_hi:[1,0]
	v_pk_mul_f32 v[88:89], v[88:89], v[136:137] op_sel_hi:[1,0]
	v_pk_mul_f32 v[90:91], v[90:91], v[136:137] op_sel_hi:[1,0]
	v_pk_mul_f32 v[84:85], v[84:85], v[136:137] op_sel_hi:[1,0]
	v_pk_mul_f32 v[86:87], v[86:87], v[136:137] op_sel_hi:[1,0]
	v_pk_mul_f32 v[120:121], v[120:121], s[78:79] op_sel_hi:[1,0]
	v_pk_mul_f32 v[122:123], v[122:123], s[78:79] op_sel_hi:[1,0]
	v_pk_mul_f32 v[116:117], v[116:117], s[78:79] op_sel_hi:[1,0]
	v_pk_mul_f32 v[118:119], v[118:119], s[78:79] op_sel_hi:[1,0]
	v_pk_mul_f32 v[88:89], v[88:89], s[78:79] op_sel_hi:[1,0]
	v_pk_mul_f32 v[90:91], v[90:91], s[78:79] op_sel_hi:[1,0]
	v_pk_mul_f32 v[84:85], v[84:85], s[78:79] op_sel_hi:[1,0]
	v_pk_mul_f32 v[86:87], v[86:87], s[78:79] op_sel_hi:[1,0]
; #define GAS __attribute__((address_space(1)))
; __host__ __device__ __forceinline__ size_t bl512(size_t row, int col) { return ((row >> 5) * 64 + (size_t)(col >> 3)) * 256 + (row & 31) * 8 + (col & 7); }
; __device__ __forceinline__ float silu_f(float v) { return v * __builtin_amdgcn_rcpf(1.0f + __builtin_amdgcn_exp2f(-v * LOG2E)); }
;     __device__ __forceinline__ void operator()(const f32x4 (&acc)[2][2][4][2], const Unit& u, int wr, int wc, int fr, int fq) const {
;     ...
;                 f32x4 v[2][2];
; #pragma unroll
;                 for (int bj = 0; bj < 2; ++bj)
; #pragma unroll
;                     for (int n = 0; n < 2; ++n) v[bj][n] = acc[ai][bj][m][n] * rs;
;                 if (sec == 4 || sec == 5) {
;                     float ss = 0.f;
; #pragma unroll
;                     for (int bj = 0; bj < 2; ++bj)
; #pragma unroll
;                         for (int n = 0; n < 2; ++n) { const f32x4 x = v[bj][n]; ss += (x[0] * x[0] + x[1] * x[1]) + (x[2] * x[2] + x[3] * x[3]); }
;                     ss = row4_sum(ss);
;                     float rn = __builtin_amdgcn_rsqf(ss * (1.0f / 64.0f) + RMS_EPS);
;                     if (sec == 4) rn *= QS;
; #pragma unroll
;                     for (int bj = 0; bj < 2; ++bj)
; #pragma unroll
;                         for (int n = 0; n < 2; ++n) v[bj][n] = v[bj][n] * rn * gain[bj][n];
;                 } else if (sec == 0) {
; #pragma unroll
;                     for (int bj = 0; bj < 2; ++bj)
; #pragma unroll
;                         for (int n = 0; n < 2; ++n) v[bj][n] = v[bj][n] * QS;
;                 } else if (sec == 3 || sec == 7) {
; #pragma unroll
;                     for (int bj = 0; bj < 2; ++bj)
; #pragma unroll
;                         for (int n = 0; n < 2; ++n)
; #pragma unroll
;                             for (int e = 0; e < 4; ++e) v[bj][n][e] = silu_f(v[bj][n][e]);
;                 }
;                 GAS f16* rowp = isqg ? QG + (size_t)dsec * QG_SEC + bl512((size_t)row, cs) : KV + (size_t)row * KVW + dsec * 512 + cs;
; #pragma unroll
;                 for (int bj = 0; bj < 2; ++bj) {
;                     u32x4 w; w.x = pkh(v[bj][0][0], v[bj][0][1]); w.y = pkh(v[bj][0][2], v[bj][0][3]); w.z = pkh(v[bj][1][0], v[bj][1][1]); w.w = pkh(v[bj][1][2], v[bj][1][3]);
;                     *(GAS u32x4*)(rowp + bjstep * bj) = w;
;                 }
	v_cvt_pk_f16_f32 v160, v120, v121
	v_cvt_pk_f16_f32 v161, v122, v123
	v_cvt_pk_f16_f32 v162, v116, v117
	v_cvt_pk_f16_f32 v163, v118, v119
	global_store_dwordx4 v133, v[160:163], s[6:7] nt
	v_cvt_pk_f16_f32 v164, v88, v89
	v_cvt_pk_f16_f32 v165, v90, v91
	v_cvt_pk_f16_f32 v166, v84, v85
	v_cvt_pk_f16_f32 v167, v86, v87
	global_store_dwordx4 v133, v[164:167], s[6:7] offset:2048 nt
	s_add_u32 s6, s4, 0x8000
	s_addc_u32 s7, s5, 0
	v_pk_mul_f32 v[112:113], v[112:113], v[138:139] op_sel_hi:[1,0]
	v_pk_mul_f32 v[114:115], v[114:115], v[138:139] op_sel_hi:[1,0]
	v_pk_mul_f32 v[108:109], v[108:109], v[138:139] op_sel_hi:[1,0]
	v_pk_mul_f32 v[110:111], v[110:111], v[138:139] op_sel_hi:[1,0]
	v_pk_mul_f32 v[80:81], v[80:81], v[138:139] op_sel_hi:[1,0]
	v_pk_mul_f32 v[82:83], v[82:83], v[138:139] op_sel_hi:[1,0]
	v_pk_mul_f32 v[76:77], v[76:77], v[138:139] op_sel_hi:[1,0]
	v_pk_mul_f32 v[78:79], v[78:79], v[138:139] op_sel_hi:[1,0]
	v_pk_mul_f32 v[112:113], v[112:113], s[78:79] op_sel_hi:[1,0]
	v_pk_mul_f32 v[114:115], v[114:115], s[78:79] op_sel_hi:[1,0]
	v_pk_mul_f32 v[108:109], v[108:109], s[78:79] op_sel_hi:[1,0]
	v_pk_mul_f32 v[110:111], v[110:111], s[78:79] op_sel_hi:[1,0]
	v_pk_mul_f32 v[80:81], v[80:81], s[78:79] op_sel_hi:[1,0]
	v_pk_mul_f32 v[82:83], v[82:83], s[78:79] op_sel_hi:[1,0]
	v_pk_mul_f32 v[76:77], v[76:77], s[78:79] op_sel_hi:[1,0]
	v_pk_mul_f32 v[78:79], v[78:79], s[78:79] op_sel_hi:[1,0]
	v_cvt_pk_f16_f32 v152, v112, v113
	v_cvt_pk_f16_f32 v153, v114, v115
	v_cvt_pk_f16_f32 v154, v108, v109
	v_cvt_pk_f16_f32 v155, v110, v111
	global_store_dwordx4 v133, v[152:155], s[6:7] nt
	v_cvt_pk_f16_f32 v156, v80, v81
	v_cvt_pk_f16_f32 v157, v82, v83
	v_cvt_pk_f16_f32 v158, v76, v77
	v_cvt_pk_f16_f32 v159, v78, v79
	global_store_dwordx4 v133, v[156:159], s[6:7] offset:2048 nt
	s_add_u32 s6, s4, 0x8100
	s_addc_u32 s7, s5, 0
	v_pk_mul_f32 v[104:105], v[104:105], v[140:141] op_sel_hi:[1,0]
	v_pk_mul_f32 v[106:107], v[106:107], v[140:141] op_sel_hi:[1,0]
	v_pk_mul_f32 v[100:101], v[100:101], v[140:141] op_sel_hi:[1,0]
	v_pk_mul_f32 v[102:103], v[102:103], v[140:141] op_sel_hi:[1,0]
	v_pk_mul_f32 v[72:73], v[72:73], v[140:141] op_sel_hi:[1,0]
	v_pk_mul_f32 v[74:75], v[74:75], v[140:141] op_sel_hi:[1,0]
	v_pk_mul_f32 v[68:69], v[68:69], v[140:141] op_sel_hi:[1,0]
	v_pk_mul_f32 v[70:71], v[70:71], v[140:141] op_sel_hi:[1,0]
	v_pk_mul_f32 v[104:105], v[104:105], s[78:79] op_sel_hi:[1,0]
	v_pk_mul_f32 v[106:107], v[106:107], s[78:79] op_sel_hi:[1,0]
	v_pk_mul_f32 v[100:101], v[100:101], s[78:79] op_sel_hi:[1,0]
	v_pk_mul_f32 v[102:103], v[102:103], s[78:79] op_sel_hi:[1,0]
	v_pk_mul_f32 v[72:73], v[72:73], s[78:79] op_sel_hi:[1,0]
	v_pk_mul_f32 v[74:75], v[74:75], s[78:79] op_sel_hi:[1,0]
	v_pk_mul_f32 v[68:69], v[68:69], s[78:79] op_sel_hi:[1,0]
	v_pk_mul_f32 v[70:71], v[70:71], s[78:79] op_sel_hi:[1,0]
	v_cvt_pk_f16_f32 v160, v104, v105
	v_cvt_pk_f16_f32 v161, v106, v107
	v_cvt_pk_f16_f32 v162, v100, v101
	v_cvt_pk_f16_f32 v163, v102, v103
	global_store_dwordx4 v133, v[160:163], s[6:7] nt
	v_cvt_pk_f16_f32 v164, v72, v73
	v_cvt_pk_f16_f32 v165, v74, v75
	v_cvt_pk_f16_f32 v166, v68, v69
	v_cvt_pk_f16_f32 v167, v70, v71
	global_store_dwordx4 v133, v[164:167], s[6:7] offset:2048 nt
	s_add_u32 s6, s4, 0x20000
	s_addc_u32 s7, s5, 0
	v_pk_mul_f32 v[64:65], v[64:65], v[142:143] op_sel_hi:[1,0]
	v_pk_mul_f32 v[66:67], v[66:67], v[142:143] op_sel_hi:[1,0]
	v_pk_mul_f32 v[60:61], v[60:61], v[142:143] op_sel_hi:[1,0]
	v_pk_mul_f32 v[62:63], v[62:63], v[142:143] op_sel_hi:[1,0]
	v_pk_mul_f32 v[32:33], v[32:33], v[142:143] op_sel_hi:[1,0]
	v_pk_mul_f32 v[34:35], v[34:35], v[142:143] op_sel_hi:[1,0]
	v_pk_mul_f32 v[28:29], v[28:29], v[142:143] op_sel_hi:[1,0]
	v_pk_mul_f32 v[30:31], v[30:31], v[142:143] op_sel_hi:[1,0]
	v_pk_mul_f32 v[64:65], v[64:65], s[78:79] op_sel_hi:[1,0]
	v_pk_mul_f32 v[66:67], v[66:67], s[78:79] op_sel_hi:[1,0]
	v_pk_mul_f32 v[60:61], v[60:61], s[78:79] op_sel_hi:[1,0]
	v_pk_mul_f32 v[62:63], v[62:63], s[78:79] op_sel_hi:[1,0]
	v_pk_mul_f32 v[32:33], v[32:33], s[78:79] op_sel_hi:[1,0]
	v_pk_mul_f32 v[34:35], v[34:35], s[78:79] op_sel_hi:[1,0]
	v_pk_mul_f32 v[28:29], v[28:29], s[78:79] op_sel_hi:[1,0]
	v_pk_mul_f32 v[30:31], v[30:31], s[78:79] op_sel_hi:[1,0]
	v_cvt_pk_f16_f32 v152, v64, v65
	v_cvt_pk_f16_f32 v153, v66, v67
	v_cvt_pk_f16_f32 v154, v60, v61
	v_cvt_pk_f16_f32 v155, v62, v63
	global_store_dwordx4 v133, v[152:155], s[6:7] nt
	v_cvt_pk_f16_f32 v156, v32, v33
	v_cvt_pk_f16_f32 v157, v34, v35
	v_cvt_pk_f16_f32 v158, v28, v29
	v_cvt_pk_f16_f32 v159, v30, v31
	global_store_dwordx4 v133, v[156:159], s[6:7] offset:2048 nt
	s_add_u32 s6, s4, 0x20100
	s_addc_u32 s7, s5, 0
	v_pk_mul_f32 v[56:57], v[56:57], v[144:145] op_sel_hi:[1,0]
	v_pk_mul_f32 v[58:59], v[58:59], v[144:145] op_sel_hi:[1,0]
	v_pk_mul_f32 v[52:53], v[52:53], v[144:145] op_sel_hi:[1,0]
	v_pk_mul_f32 v[54:55], v[54:55], v[144:145] op_sel_hi:[1,0]
	v_pk_mul_f32 v[24:25], v[24:25], v[144:145] op_sel_hi:[1,0]
	v_pk_mul_f32 v[26:27], v[26:27], v[144:145] op_sel_hi:[1,0]
	v_pk_mul_f32 v[20:21], v[20:21], v[144:145] op_sel_hi:[1,0]
	v_pk_mul_f32 v[22:23], v[22:23], v[144:145] op_sel_hi:[1,0]
	v_pk_mul_f32 v[56:57], v[56:57], s[78:79] op_sel_hi:[1,0]
	v_pk_mul_f32 v[58:59], v[58:59], s[78:79] op_sel_hi:[1,0]
	v_pk_mul_f32 v[52:53], v[52:53], s[78:79] op_sel_hi:[1,0]
	v_pk_mul_f32 v[54:55], v[54:55], s[78:79] op_sel_hi:[1,0]
	v_pk_mul_f32 v[24:25], v[24:25], s[78:79] op_sel_hi:[1,0]
	v_pk_mul_f32 v[26:27], v[26:27], s[78:79] op_sel_hi:[1,0]
	v_pk_mul_f32 v[20:21], v[20:21], s[78:79] op_sel_hi:[1,0]
	v_pk_mul_f32 v[22:23], v[22:23], s[78:79] op_sel_hi:[1,0]
; #define GAS __attribute__((address_space(1)))
; __host__ __device__ __forceinline__ size_t bl512(size_t row, int col) { return ((row >> 5) * 64 + (size_t)(col >> 3)) * 256 + (row & 31) * 8 + (col & 7); }
; __device__ __forceinline__ float silu_f(float v) { return v * __builtin_amdgcn_rcpf(1.0f + __builtin_amdgcn_exp2f(-v * LOG2E)); }
;     __device__ __forceinline__ void operator()(const f32x4 (&acc)[2][2][4][2], const Unit& u, int wr, int wc, int fr, int fq) const {
;     ...
;                 } else if (sec == 0) {
; #pragma unroll
;                     for (int bj = 0; bj < 2; ++bj)
; #pragma unroll
;                         for (int n = 0; n < 2; ++n) v[bj][n] = v[bj][n] * QS;
;                 } else if (sec == 3 || sec == 7) {
; #pragma unroll
;                     for (int bj = 0; bj < 2; ++bj)
; #pragma unroll
;                         for (int n = 0; n < 2; ++n)
; #pragma unroll
;                             for (int e = 0; e < 4; ++e) v[bj][n][e] = silu_f(v[bj][n][e]);
;                 }
;                 GAS f16* rowp = isqg ? QG + (size_t)dsec * QG_SEC + bl512((size_t)row, cs) : KV + (size_t)row * KVW + dsec * 512 + cs;
; #pragma unroll
;                 for (int bj = 0; bj < 2; ++bj) {
;                     u32x4 w; w.x = pkh(v[bj][0][0], v[bj][0][1]); w.y = pkh(v[bj][0][2], v[bj][0][3]); w.z = pkh(v[bj][1][0], v[bj][1][1]); w.w = pkh(v[bj][1][2], v[bj][1][3]);
;                     *(GAS u32x4*)(rowp + bjstep * bj) = w;
;                 }
	v_cvt_pk_f16_f32 v160, v56, v57
	v_cvt_pk_f16_f32 v161, v58, v59
	v_cvt_pk_f16_f32 v162, v52, v53
	v_cvt_pk_f16_f32 v163, v54, v55
	global_store_dwordx4 v133, v[160:163], s[6:7] nt
	v_cvt_pk_f16_f32 v164, v24, v25
	v_cvt_pk_f16_f32 v165, v26, v27
	v_cvt_pk_f16_f32 v166, v20, v21
	v_cvt_pk_f16_f32 v167, v22, v23
	global_store_dwordx4 v133, v[164:167], s[6:7] offset:2048 nt
	s_add_u32 s6, s4, 0x28000
	s_addc_u32 s7, s5, 0
	v_pk_mul_f32 v[48:49], v[48:49], v[146:147] op_sel_hi:[1,0]
	v_pk_mul_f32 v[50:51], v[50:51], v[146:147] op_sel_hi:[1,0]
	v_pk_mul_f32 v[44:45], v[44:45], v[146:147] op_sel_hi:[1,0]
	v_pk_mul_f32 v[46:47], v[46:47], v[146:147] op_sel_hi:[1,0]
	v_pk_mul_f32 v[16:17], v[16:17], v[146:147] op_sel_hi:[1,0]
	v_pk_mul_f32 v[18:19], v[18:19], v[146:147] op_sel_hi:[1,0]
	v_pk_mul_f32 v[12:13], v[12:13], v[146:147] op_sel_hi:[1,0]
	v_pk_mul_f32 v[14:15], v[14:15], v[146:147] op_sel_hi:[1,0]
	v_pk_mul_f32 v[48:49], v[48:49], s[78:79] op_sel_hi:[1,0]
	v_pk_mul_f32 v[50:51], v[50:51], s[78:79] op_sel_hi:[1,0]
	v_pk_mul_f32 v[44:45], v[44:45], s[78:79] op_sel_hi:[1,0]
	v_pk_mul_f32 v[46:47], v[46:47], s[78:79] op_sel_hi:[1,0]
	v_pk_mul_f32 v[16:17], v[16:17], s[78:79] op_sel_hi:[1,0]
	v_pk_mul_f32 v[18:19], v[18:19], s[78:79] op_sel_hi:[1,0]
	v_pk_mul_f32 v[12:13], v[12:13], s[78:79] op_sel_hi:[1,0]
	v_pk_mul_f32 v[14:15], v[14:15], s[78:79] op_sel_hi:[1,0]
	v_cvt_pk_f16_f32 v152, v48, v49
	v_cvt_pk_f16_f32 v153, v50, v51
	v_cvt_pk_f16_f32 v154, v44, v45
	v_cvt_pk_f16_f32 v155, v46, v47
	global_store_dwordx4 v133, v[152:155], s[6:7] nt
	v_cvt_pk_f16_f32 v156, v16, v17
	v_cvt_pk_f16_f32 v157, v18, v19
	v_cvt_pk_f16_f32 v158, v12, v13
	v_cvt_pk_f16_f32 v159, v14, v15
	global_store_dwordx4 v133, v[156:159], s[6:7] offset:2048 nt
	s_add_u32 s6, s4, 0x28100
	s_addc_u32 s7, s5, 0
	v_pk_mul_f32 v[40:41], v[40:41], v[148:149] op_sel_hi:[1,0]
	v_pk_mul_f32 v[42:43], v[42:43], v[148:149] op_sel_hi:[1,0]
	v_pk_mul_f32 v[36:37], v[36:37], v[148:149] op_sel_hi:[1,0]
	v_pk_mul_f32 v[38:39], v[38:39], v[148:149] op_sel_hi:[1,0]
	v_pk_mul_f32 v[8:9], v[8:9], v[148:149] op_sel_hi:[1,0]
	v_pk_mul_f32 v[10:11], v[10:11], v[148:149] op_sel_hi:[1,0]
	v_pk_mul_f32 v[4:5], v[4:5], v[148:149] op_sel_hi:[1,0]
	v_pk_mul_f32 v[6:7], v[6:7], v[148:149] op_sel_hi:[1,0]
	v_pk_mul_f32 v[40:41], v[40:41], s[78:79] op_sel_hi:[1,0]
	v_pk_mul_f32 v[42:43], v[42:43], s[78:79] op_sel_hi:[1,0]
	v_pk_mul_f32 v[36:37], v[36:37], s[78:79] op_sel_hi:[1,0]
	v_pk_mul_f32 v[38:39], v[38:39], s[78:79] op_sel_hi:[1,0]
	v_pk_mul_f32 v[8:9], v[8:9], s[78:79] op_sel_hi:[1,0]
	v_pk_mul_f32 v[10:11], v[10:11], s[78:79] op_sel_hi:[1,0]
	v_pk_mul_f32 v[4:5], v[4:5], s[78:79] op_sel_hi:[1,0]
	v_pk_mul_f32 v[6:7], v[6:7], s[78:79] op_sel_hi:[1,0]
	v_cvt_pk_f16_f32 v160, v40, v41
	v_cvt_pk_f16_f32 v161, v42, v43
	v_cvt_pk_f16_f32 v162, v36, v37
	v_cvt_pk_f16_f32 v163, v38, v39
	global_store_dwordx4 v133, v[160:163], s[6:7] nt
	v_cvt_pk_f16_f32 v164, v8, v9
	v_cvt_pk_f16_f32 v165, v10, v11
	v_cvt_pk_f16_f32 v166, v4, v5
	v_cvt_pk_f16_f32 v167, v6, v7
	global_store_dwordx4 v133, v[164:167], s[6:7] offset:2048 nt
	s_branch .Lepi_done_g1
.Lepi_silu:
	s_and_b32 s0, s70, 1
	s_lshl_b32 s0, s0, 10
	v_add_u32_e32 v132, s0, v219
	ds_read_b32 v134, v132
	ds_read_b32 v136, v132 offset:64
	ds_read_b32 v138, v132 offset:128
	ds_read_b32 v140, v132 offset:192
	ds_read_b32 v142, v132 offset:512
	ds_read_b32 v144, v132 offset:576
	ds_read_b32 v146, v132 offset:640
	ds_read_b32 v148, v132 offset:704
	s_lshr_b32 s0, s69, 2
	s_and_b32 s1, s69, 1
	v_lshrrev_b32_e32 v2, 6, v187
	v_lshrrev_b32_e32 v133, 3, v220
	v_lshl_add_u32 v133, v2, 7, v133
	v_and_b32_e32 v2, 15, v187
	v_lshlrev_b32_e32 v133, 8, v133
	v_lshl_add_u32 v133, v2, 3, v133
	v_lshlrev_b32_e32 v133, 1, v133
	s_lshl_b32 s0, s0, 25
	s_lshl_b32 s1, s1, 14
	s_add_u32 s0, s0, s1
	s_lshl_b32 s1, s68, 18
	s_add_u32 s0, s0, s1
	s_add_u32 s4, s82, s0
	s_addc_u32 s5, s83, 0
	s_waitcnt lgkmcnt(0)
	s_mov_b32 s6, s4
	s_mov_b32 s7, s5
	v_pk_mul_f32 v[128:129], v[128:129], v[134:135] op_sel_hi:[1,0]
	v_pk_mul_f32 v[130:131], v[130:131], v[134:135] op_sel_hi:[1,0]
	v_pk_mul_f32 v[124:125], v[124:125], v[134:135] op_sel_hi:[1,0]
	v_pk_mul_f32 v[126:127], v[126:127], v[134:135] op_sel_hi:[1,0]
	v_pk_mul_f32 v[96:97], v[96:97], v[134:135] op_sel_hi:[1,0]
	v_pk_mul_f32 v[98:99], v[98:99], v[134:135] op_sel_hi:[1,0]
	v_pk_mul_f32 v[92:93], v[92:93], v[134:135] op_sel_hi:[1,0]
	v_pk_mul_f32 v[94:95], v[94:95], v[134:135] op_sel_hi:[1,0]
	v_mul_f32_e32 v168, 0xbfb8aa3b, v128
	v_mul_f32_e32 v169, 0xbfb8aa3b, v129
	v_mul_f32_e32 v170, 0xbfb8aa3b, v130
	v_mul_f32_e32 v171, 0xbfb8aa3b, v131
	v_exp_f32_e32 v168, v168
	v_exp_f32_e32 v169, v169
	v_exp_f32_e32 v170, v170
	v_exp_f32_e32 v171, v171
	v_add_f32_e32 v168, 1.0, v168
	v_add_f32_e32 v169, 1.0, v169
	v_add_f32_e32 v170, 1.0, v170
	v_add_f32_e32 v171, 1.0, v171
	v_rcp_f32_e32 v168, v168
	v_rcp_f32_e32 v169, v169
	v_rcp_f32_e32 v170, v170
	v_rcp_f32_e32 v171, v171
	v_pk_mul_f32 v[128:129], v[128:129], v[168:169]
	v_pk_mul_f32 v[130:131], v[130:131], v[170:171]
	v_mul_f32_e32 v168, 0xbfb8aa3b, v124
	v_mul_f32_e32 v169, 0xbfb8aa3b, v125
	v_mul_f32_e32 v170, 0xbfb8aa3b, v126
	v_mul_f32_e32 v171, 0xbfb8aa3b, v127
	v_exp_f32_e32 v168, v168
	v_exp_f32_e32 v169, v169
	v_exp_f32_e32 v170, v170
	v_exp_f32_e32 v171, v171
	v_add_f32_e32 v168, 1.0, v168
	v_add_f32_e32 v169, 1.0, v169
	v_add_f32_e32 v170, 1.0, v170
	v_add_f32_e32 v171, 1.0, v171
	v_rcp_f32_e32 v168, v168
	v_rcp_f32_e32 v169, v169
	v_rcp_f32_e32 v170, v170
	v_rcp_f32_e32 v171, v171
	v_pk_mul_f32 v[124:125], v[124:125], v[168:169]
	v_pk_mul_f32 v[126:127], v[126:127], v[170:171]
; #define GAS __attribute__((address_space(1)))
; __host__ __device__ __forceinline__ size_t bl512(size_t row, int col) { return ((row >> 5) * 64 + (size_t)(col >> 3)) * 256 + (row & 31) * 8 + (col & 7); }
; __device__ __forceinline__ float silu_f(float v) { return v * __builtin_amdgcn_rcpf(1.0f + __builtin_amdgcn_exp2f(-v * LOG2E)); }
;     __device__ __forceinline__ void operator()(const f32x4 (&acc)[2][2][4][2], const Unit& u, int wr, int wc, int fr, int fq) const {
;     ...
;                 } else if (sec == 3 || sec == 7) {
; #pragma unroll
;                     for (int bj = 0; bj < 2; ++bj)
; #pragma unroll
;                         for (int n = 0; n < 2; ++n)
; #pragma unroll
;                             for (int e = 0; e < 4; ++e) v[bj][n][e] = silu_f(v[bj][n][e]);
;                 }
;                 GAS f16* rowp = isqg ? QG + (size_t)dsec * QG_SEC + bl512((size_t)row, cs) : KV + (size_t)row * KVW + dsec * 512 + cs;
; #pragma unroll
;                 for (int bj = 0; bj < 2; ++bj) {
;                     u32x4 w; w.x = pkh(v[bj][0][0], v[bj][0][1]); w.y = pkh(v[bj][0][2], v[bj][0][3]); w.z = pkh(v[bj][1][0], v[bj][1][1]); w.w = pkh(v[bj][1][2], v[bj][1][3]);
;                     *(GAS u32x4*)(rowp + bjstep * bj) = w;
;                 }
	v_mul_f32_e32 v168, 0xbfb8aa3b, v96
	v_mul_f32_e32 v169, 0xbfb8aa3b, v97
	v_mul_f32_e32 v170, 0xbfb8aa3b, v98
	v_mul_f32_e32 v171, 0xbfb8aa3b, v99
	v_exp_f32_e32 v168, v168
	v_exp_f32_e32 v169, v169
	v_exp_f32_e32 v170, v170
	v_exp_f32_e32 v171, v171
	v_add_f32_e32 v168, 1.0, v168
	v_add_f32_e32 v169, 1.0, v169
	v_add_f32_e32 v170, 1.0, v170
	v_add_f32_e32 v171, 1.0, v171
	v_rcp_f32_e32 v168, v168
	v_rcp_f32_e32 v169, v169
	v_rcp_f32_e32 v170, v170
	v_rcp_f32_e32 v171, v171
	v_pk_mul_f32 v[96:97], v[96:97], v[168:169]
	v_pk_mul_f32 v[98:99], v[98:99], v[170:171]
	v_mul_f32_e32 v168, 0xbfb8aa3b, v92
	v_mul_f32_e32 v169, 0xbfb8aa3b, v93
	v_mul_f32_e32 v170, 0xbfb8aa3b, v94
	v_mul_f32_e32 v171, 0xbfb8aa3b, v95
	v_exp_f32_e32 v168, v168
	v_exp_f32_e32 v169, v169
	v_exp_f32_e32 v170, v170
	v_exp_f32_e32 v171, v171
	v_add_f32_e32 v168, 1.0, v168
	v_add_f32_e32 v169, 1.0, v169
	v_add_f32_e32 v170, 1.0, v170
	v_add_f32_e32 v171, 1.0, v171
	v_rcp_f32_e32 v168, v168
	v_rcp_f32_e32 v169, v169
	v_rcp_f32_e32 v170, v170
	v_rcp_f32_e32 v171, v171
	v_pk_mul_f32 v[92:93], v[92:93], v[168:169]
	v_pk_mul_f32 v[94:95], v[94:95], v[170:171]
	v_cvt_pk_f16_f32 v152, v128, v129
	v_cvt_pk_f16_f32 v153, v130, v131
	v_cvt_pk_f16_f32 v154, v124, v125
	v_cvt_pk_f16_f32 v155, v126, v127
	global_store_dwordx4 v133, v[152:155], s[6:7] nt
	v_cvt_pk_f16_f32 v156, v96, v97
	v_cvt_pk_f16_f32 v157, v98, v99
	v_cvt_pk_f16_f32 v158, v92, v93
	v_cvt_pk_f16_f32 v159, v94, v95
	global_store_dwordx4 v133, v[156:159], s[6:7] offset:2048 nt
	s_add_u32 s6, s4, 0x100
	s_addc_u32 s7, s5, 0
	v_pk_mul_f32 v[120:121], v[120:121], v[136:137] op_sel_hi:[1,0]
	v_pk_mul_f32 v[122:123], v[122:123], v[136:137] op_sel_hi:[1,0]
	v_pk_mul_f32 v[116:117], v[116:117], v[136:137] op_sel_hi:[1,0]
	v_pk_mul_f32 v[118:119], v[118:119], v[136:137] op_sel_hi:[1,0]
	v_pk_mul_f32 v[88:89], v[88:89], v[136:137] op_sel_hi:[1,0]
	v_pk_mul_f32 v[90:91], v[90:91], v[136:137] op_sel_hi:[1,0]
	v_pk_mul_f32 v[84:85], v[84:85], v[136:137] op_sel_hi:[1,0]
	v_pk_mul_f32 v[86:87], v[86:87], v[136:137] op_sel_hi:[1,0]
	v_mul_f32_e32 v168, 0xbfb8aa3b, v120
	v_mul_f32_e32 v169, 0xbfb8aa3b, v121
	v_mul_f32_e32 v170, 0xbfb8aa3b, v122
	v_mul_f32_e32 v171, 0xbfb8aa3b, v123
	v_exp_f32_e32 v168, v168
	v_exp_f32_e32 v169, v169
	v_exp_f32_e32 v170, v170
	v_exp_f32_e32 v171, v171
	v_add_f32_e32 v168, 1.0, v168
	v_add_f32_e32 v169, 1.0, v169
	v_add_f32_e32 v170, 1.0, v170
	v_add_f32_e32 v171, 1.0, v171
	v_rcp_f32_e32 v168, v168
	v_rcp_f32_e32 v169, v169
	v_rcp_f32_e32 v170, v170
	v_rcp_f32_e32 v171, v171
	v_pk_mul_f32 v[120:121], v[120:121], v[168:169]
	v_pk_mul_f32 v[122:123], v[122:123], v[170:171]
	v_mul_f32_e32 v168, 0xbfb8aa3b, v116
	v_mul_f32_e32 v169, 0xbfb8aa3b, v117
	v_mul_f32_e32 v170, 0xbfb8aa3b, v118
	v_mul_f32_e32 v171, 0xbfb8aa3b, v119
	v_exp_f32_e32 v168, v168
	v_exp_f32_e32 v169, v169
	v_exp_f32_e32 v170, v170
	v_exp_f32_e32 v171, v171
	v_add_f32_e32 v168, 1.0, v168
	v_add_f32_e32 v169, 1.0, v169
	v_add_f32_e32 v170, 1.0, v170
	v_add_f32_e32 v171, 1.0, v171
	v_rcp_f32_e32 v168, v168
	v_rcp_f32_e32 v169, v169
	v_rcp_f32_e32 v170, v170
	v_rcp_f32_e32 v171, v171
	v_pk_mul_f32 v[116:117], v[116:117], v[168:169]
	v_pk_mul_f32 v[118:119], v[118:119], v[170:171]
	v_mul_f32_e32 v168, 0xbfb8aa3b, v88
	v_mul_f32_e32 v169, 0xbfb8aa3b, v89
	v_mul_f32_e32 v170, 0xbfb8aa3b, v90
	v_mul_f32_e32 v171, 0xbfb8aa3b, v91
	v_exp_f32_e32 v168, v168
	v_exp_f32_e32 v169, v169
	v_exp_f32_e32 v170, v170
	v_exp_f32_e32 v171, v171
	v_add_f32_e32 v168, 1.0, v168
	v_add_f32_e32 v169, 1.0, v169
	v_add_f32_e32 v170, 1.0, v170
	v_add_f32_e32 v171, 1.0, v171
	v_rcp_f32_e32 v168, v168
	v_rcp_f32_e32 v169, v169
	v_rcp_f32_e32 v170, v170
	v_rcp_f32_e32 v171, v171
	v_pk_mul_f32 v[88:89], v[88:89], v[168:169]
	v_pk_mul_f32 v[90:91], v[90:91], v[170:171]
	v_mul_f32_e32 v168, 0xbfb8aa3b, v84
	v_mul_f32_e32 v169, 0xbfb8aa3b, v85
	v_mul_f32_e32 v170, 0xbfb8aa3b, v86
	v_mul_f32_e32 v171, 0xbfb8aa3b, v87
	v_exp_f32_e32 v168, v168
	v_exp_f32_e32 v169, v169
	v_exp_f32_e32 v170, v170
	v_exp_f32_e32 v171, v171
	v_add_f32_e32 v168, 1.0, v168
	v_add_f32_e32 v169, 1.0, v169
	v_add_f32_e32 v170, 1.0, v170
	v_add_f32_e32 v171, 1.0, v171
	v_rcp_f32_e32 v168, v168
	v_rcp_f32_e32 v169, v169
	v_rcp_f32_e32 v170, v170
	v_rcp_f32_e32 v171, v171
	v_pk_mul_f32 v[84:85], v[84:85], v[168:169]
	v_pk_mul_f32 v[86:87], v[86:87], v[170:171]
	v_cvt_pk_f16_f32 v160, v120, v121
	v_cvt_pk_f16_f32 v161, v122, v123
	v_cvt_pk_f16_f32 v162, v116, v117
	v_cvt_pk_f16_f32 v163, v118, v119
	global_store_dwordx4 v133, v[160:163], s[6:7] nt
	v_cvt_pk_f16_f32 v164, v88, v89
	v_cvt_pk_f16_f32 v165, v90, v91
	v_cvt_pk_f16_f32 v166, v84, v85
	v_cvt_pk_f16_f32 v167, v86, v87
	global_store_dwordx4 v133, v[164:167], s[6:7] offset:2048 nt
	s_add_u32 s6, s4, 0x8000
	s_addc_u32 s7, s5, 0
	v_pk_mul_f32 v[112:113], v[112:113], v[138:139] op_sel_hi:[1,0]
	v_pk_mul_f32 v[114:115], v[114:115], v[138:139] op_sel_hi:[1,0]
	v_pk_mul_f32 v[108:109], v[108:109], v[138:139] op_sel_hi:[1,0]
	v_pk_mul_f32 v[110:111], v[110:111], v[138:139] op_sel_hi:[1,0]
	v_pk_mul_f32 v[80:81], v[80:81], v[138:139] op_sel_hi:[1,0]
	v_pk_mul_f32 v[82:83], v[82:83], v[138:139] op_sel_hi:[1,0]
	v_pk_mul_f32 v[76:77], v[76:77], v[138:139] op_sel_hi:[1,0]
	v_pk_mul_f32 v[78:79], v[78:79], v[138:139] op_sel_hi:[1,0]
	v_mul_f32_e32 v168, 0xbfb8aa3b, v112
	v_mul_f32_e32 v169, 0xbfb8aa3b, v113
	v_mul_f32_e32 v170, 0xbfb8aa3b, v114
	v_mul_f32_e32 v171, 0xbfb8aa3b, v115
	v_exp_f32_e32 v168, v168
	v_exp_f32_e32 v169, v169
	v_exp_f32_e32 v170, v170
	v_exp_f32_e32 v171, v171
	v_add_f32_e32 v168, 1.0, v168
	v_add_f32_e32 v169, 1.0, v169
; #define GAS __attribute__((address_space(1)))
; __host__ __device__ __forceinline__ size_t bl512(size_t row, int col) { return ((row >> 5) * 64 + (size_t)(col >> 3)) * 256 + (row & 31) * 8 + (col & 7); }
; __device__ __forceinline__ float silu_f(float v) { return v * __builtin_amdgcn_rcpf(1.0f + __builtin_amdgcn_exp2f(-v * LOG2E)); }
;     __device__ __forceinline__ void operator()(const f32x4 (&acc)[2][2][4][2], const Unit& u, int wr, int wc, int fr, int fq) const {
;     ...
;                 } else if (sec == 3 || sec == 7) {
; #pragma unroll
;                     for (int bj = 0; bj < 2; ++bj)
; #pragma unroll
;                         for (int n = 0; n < 2; ++n)
; #pragma unroll
;                             for (int e = 0; e < 4; ++e) v[bj][n][e] = silu_f(v[bj][n][e]);
;                 }
;                 GAS f16* rowp = isqg ? QG + (size_t)dsec * QG_SEC + bl512((size_t)row, cs) : KV + (size_t)row * KVW + dsec * 512 + cs;
; #pragma unroll
;                 for (int bj = 0; bj < 2; ++bj) {
;                     u32x4 w; w.x = pkh(v[bj][0][0], v[bj][0][1]); w.y = pkh(v[bj][0][2], v[bj][0][3]); w.z = pkh(v[bj][1][0], v[bj][1][1]); w.w = pkh(v[bj][1][2], v[bj][1][3]);
;                     *(GAS u32x4*)(rowp + bjstep * bj) = w;
;                 }
	v_add_f32_e32 v170, 1.0, v170
	v_add_f32_e32 v171, 1.0, v171
	v_rcp_f32_e32 v168, v168
	v_rcp_f32_e32 v169, v169
	v_rcp_f32_e32 v170, v170
	v_rcp_f32_e32 v171, v171
	v_pk_mul_f32 v[112:113], v[112:113], v[168:169]
	v_pk_mul_f32 v[114:115], v[114:115], v[170:171]
	v_mul_f32_e32 v168, 0xbfb8aa3b, v108
	v_mul_f32_e32 v169, 0xbfb8aa3b, v109
	v_mul_f32_e32 v170, 0xbfb8aa3b, v110
	v_mul_f32_e32 v171, 0xbfb8aa3b, v111
	v_exp_f32_e32 v168, v168
	v_exp_f32_e32 v169, v169
	v_exp_f32_e32 v170, v170
	v_exp_f32_e32 v171, v171
	v_add_f32_e32 v168, 1.0, v168
	v_add_f32_e32 v169, 1.0, v169
	v_add_f32_e32 v170, 1.0, v170
	v_add_f32_e32 v171, 1.0, v171
	v_rcp_f32_e32 v168, v168
	v_rcp_f32_e32 v169, v169
	v_rcp_f32_e32 v170, v170
	v_rcp_f32_e32 v171, v171
	v_pk_mul_f32 v[108:109], v[108:109], v[168:169]
	v_pk_mul_f32 v[110:111], v[110:111], v[170:171]
	v_mul_f32_e32 v168, 0xbfb8aa3b, v80
	v_mul_f32_e32 v169, 0xbfb8aa3b, v81
	v_mul_f32_e32 v170, 0xbfb8aa3b, v82
	v_mul_f32_e32 v171, 0xbfb8aa3b, v83
	v_exp_f32_e32 v168, v168
	v_exp_f32_e32 v169, v169
	v_exp_f32_e32 v170, v170
	v_exp_f32_e32 v171, v171
	v_add_f32_e32 v168, 1.0, v168
	v_add_f32_e32 v169, 1.0, v169
	v_add_f32_e32 v170, 1.0, v170
	v_add_f32_e32 v171, 1.0, v171
	v_rcp_f32_e32 v168, v168
	v_rcp_f32_e32 v169, v169
	v_rcp_f32_e32 v170, v170
	v_rcp_f32_e32 v171, v171
	v_pk_mul_f32 v[80:81], v[80:81], v[168:169]
	v_pk_mul_f32 v[82:83], v[82:83], v[170:171]
	v_mul_f32_e32 v168, 0xbfb8aa3b, v76
	v_mul_f32_e32 v169, 0xbfb8aa3b, v77
	v_mul_f32_e32 v170, 0xbfb8aa3b, v78
	v_mul_f32_e32 v171, 0xbfb8aa3b, v79
	v_exp_f32_e32 v168, v168
	v_exp_f32_e32 v169, v169
	v_exp_f32_e32 v170, v170
	v_exp_f32_e32 v171, v171
	v_add_f32_e32 v168, 1.0, v168
	v_add_f32_e32 v169, 1.0, v169
	v_add_f32_e32 v170, 1.0, v170
	v_add_f32_e32 v171, 1.0, v171
	v_rcp_f32_e32 v168, v168
	v_rcp_f32_e32 v169, v169
	v_rcp_f32_e32 v170, v170
	v_rcp_f32_e32 v171, v171
	v_pk_mul_f32 v[76:77], v[76:77], v[168:169]
	v_pk_mul_f32 v[78:79], v[78:79], v[170:171]
	v_cvt_pk_f16_f32 v152, v112, v113
	v_cvt_pk_f16_f32 v153, v114, v115
	v_cvt_pk_f16_f32 v154, v108, v109
	v_cvt_pk_f16_f32 v155, v110, v111
	global_store_dwordx4 v133, v[152:155], s[6:7] nt
	v_cvt_pk_f16_f32 v156, v80, v81
	v_cvt_pk_f16_f32 v157, v82, v83
	v_cvt_pk_f16_f32 v158, v76, v77
	v_cvt_pk_f16_f32 v159, v78, v79
	global_store_dwordx4 v133, v[156:159], s[6:7] offset:2048 nt
	s_add_u32 s6, s4, 0x8100
	s_addc_u32 s7, s5, 0
	v_pk_mul_f32 v[104:105], v[104:105], v[140:141] op_sel_hi:[1,0]
	v_pk_mul_f32 v[106:107], v[106:107], v[140:141] op_sel_hi:[1,0]
	v_pk_mul_f32 v[100:101], v[100:101], v[140:141] op_sel_hi:[1,0]
	v_pk_mul_f32 v[102:103], v[102:103], v[140:141] op_sel_hi:[1,0]
	v_pk_mul_f32 v[72:73], v[72:73], v[140:141] op_sel_hi:[1,0]
	v_pk_mul_f32 v[74:75], v[74:75], v[140:141] op_sel_hi:[1,0]
	v_pk_mul_f32 v[68:69], v[68:69], v[140:141] op_sel_hi:[1,0]
	v_pk_mul_f32 v[70:71], v[70:71], v[140:141] op_sel_hi:[1,0]
	v_mul_f32_e32 v168, 0xbfb8aa3b, v104
	v_mul_f32_e32 v169, 0xbfb8aa3b, v105
	v_mul_f32_e32 v170, 0xbfb8aa3b, v106
	v_mul_f32_e32 v171, 0xbfb8aa3b, v107
	v_exp_f32_e32 v168, v168
	v_exp_f32_e32 v169, v169
	v_exp_f32_e32 v170, v170
	v_exp_f32_e32 v171, v171
	v_add_f32_e32 v168, 1.0, v168
	v_add_f32_e32 v169, 1.0, v169
	v_add_f32_e32 v170, 1.0, v170
	v_add_f32_e32 v171, 1.0, v171
	v_rcp_f32_e32 v168, v168
	v_rcp_f32_e32 v169, v169
	v_rcp_f32_e32 v170, v170
	v_rcp_f32_e32 v171, v171
	v_pk_mul_f32 v[104:105], v[104:105], v[168:169]
	v_pk_mul_f32 v[106:107], v[106:107], v[170:171]
	v_mul_f32_e32 v168, 0xbfb8aa3b, v100
	v_mul_f32_e32 v169, 0xbfb8aa3b, v101
	v_mul_f32_e32 v170, 0xbfb8aa3b, v102
	v_mul_f32_e32 v171, 0xbfb8aa3b, v103
	v_exp_f32_e32 v168, v168
	v_exp_f32_e32 v169, v169
	v_exp_f32_e32 v170, v170
	v_exp_f32_e32 v171, v171
	v_add_f32_e32 v168, 1.0, v168
	v_add_f32_e32 v169, 1.0, v169
	v_add_f32_e32 v170, 1.0, v170
	v_add_f32_e32 v171, 1.0, v171
	v_rcp_f32_e32 v168, v168
	v_rcp_f32_e32 v169, v169
	v_rcp_f32_e32 v170, v170
	v_rcp_f32_e32 v171, v171
	v_pk_mul_f32 v[100:101], v[100:101], v[168:169]
	v_pk_mul_f32 v[102:103], v[102:103], v[170:171]
	v_mul_f32_e32 v168, 0xbfb8aa3b, v72
	v_mul_f32_e32 v169, 0xbfb8aa3b, v73
	v_mul_f32_e32 v170, 0xbfb8aa3b, v74
	v_mul_f32_e32 v171, 0xbfb8aa3b, v75
	v_exp_f32_e32 v168, v168
	v_exp_f32_e32 v169, v169
	v_exp_f32_e32 v170, v170
	v_exp_f32_e32 v171, v171
	v_add_f32_e32 v168, 1.0, v168
	v_add_f32_e32 v169, 1.0, v169
	v_add_f32_e32 v170, 1.0, v170
	v_add_f32_e32 v171, 1.0, v171
	v_rcp_f32_e32 v168, v168
	v_rcp_f32_e32 v169, v169
	v_rcp_f32_e32 v170, v170
	v_rcp_f32_e32 v171, v171
	v_pk_mul_f32 v[72:73], v[72:73], v[168:169]
	v_pk_mul_f32 v[74:75], v[74:75], v[170:171]
	v_mul_f32_e32 v168, 0xbfb8aa3b, v68
	v_mul_f32_e32 v169, 0xbfb8aa3b, v69
	v_mul_f32_e32 v170, 0xbfb8aa3b, v70
	v_mul_f32_e32 v171, 0xbfb8aa3b, v71
	v_exp_f32_e32 v168, v168
	v_exp_f32_e32 v169, v169
	v_exp_f32_e32 v170, v170
	v_exp_f32_e32 v171, v171
	v_add_f32_e32 v168, 1.0, v168
	v_add_f32_e32 v169, 1.0, v169
	v_add_f32_e32 v170, 1.0, v170
	v_add_f32_e32 v171, 1.0, v171
	v_rcp_f32_e32 v168, v168
	v_rcp_f32_e32 v169, v169
	v_rcp_f32_e32 v170, v170
	v_rcp_f32_e32 v171, v171
	v_pk_mul_f32 v[68:69], v[68:69], v[168:169]
	v_pk_mul_f32 v[70:71], v[70:71], v[170:171]
	v_cvt_pk_f16_f32 v160, v104, v105
	v_cvt_pk_f16_f32 v161, v106, v107
	v_cvt_pk_f16_f32 v162, v100, v101
	v_cvt_pk_f16_f32 v163, v102, v103
	global_store_dwordx4 v133, v[160:163], s[6:7] nt
	v_cvt_pk_f16_f32 v164, v72, v73
	v_cvt_pk_f16_f32 v165, v74, v75
	v_cvt_pk_f16_f32 v166, v68, v69
	v_cvt_pk_f16_f32 v167, v70, v71
	global_store_dwordx4 v133, v[164:167], s[6:7] offset:2048 nt
	s_add_u32 s6, s4, 0x20000
; #define GAS __attribute__((address_space(1)))
; __host__ __device__ __forceinline__ size_t bl512(size_t row, int col) { return ((row >> 5) * 64 + (size_t)(col >> 3)) * 256 + (row & 31) * 8 + (col & 7); }
; __device__ __forceinline__ float silu_f(float v) { return v * __builtin_amdgcn_rcpf(1.0f + __builtin_amdgcn_exp2f(-v * LOG2E)); }
;     __device__ __forceinline__ void operator()(const f32x4 (&acc)[2][2][4][2], const Unit& u, int wr, int wc, int fr, int fq) const {
;     ...
;                 } else if (sec == 3 || sec == 7) {
; #pragma unroll
;                     for (int bj = 0; bj < 2; ++bj)
; #pragma unroll
;                         for (int n = 0; n < 2; ++n)
; #pragma unroll
;                             for (int e = 0; e < 4; ++e) v[bj][n][e] = silu_f(v[bj][n][e]);
;                 }
;                 GAS f16* rowp = isqg ? QG + (size_t)dsec * QG_SEC + bl512((size_t)row, cs) : KV + (size_t)row * KVW + dsec * 512 + cs;
; #pragma unroll
;                 for (int bj = 0; bj < 2; ++bj) {
;                     u32x4 w; w.x = pkh(v[bj][0][0], v[bj][0][1]); w.y = pkh(v[bj][0][2], v[bj][0][3]); w.z = pkh(v[bj][1][0], v[bj][1][1]); w.w = pkh(v[bj][1][2], v[bj][1][3]);
;                     *(GAS u32x4*)(rowp + bjstep * bj) = w;
;                 }
	s_addc_u32 s7, s5, 0
	v_pk_mul_f32 v[64:65], v[64:65], v[142:143] op_sel_hi:[1,0]
	v_pk_mul_f32 v[66:67], v[66:67], v[142:143] op_sel_hi:[1,0]
	v_pk_mul_f32 v[60:61], v[60:61], v[142:143] op_sel_hi:[1,0]
	v_pk_mul_f32 v[62:63], v[62:63], v[142:143] op_sel_hi:[1,0]
	v_pk_mul_f32 v[32:33], v[32:33], v[142:143] op_sel_hi:[1,0]
	v_pk_mul_f32 v[34:35], v[34:35], v[142:143] op_sel_hi:[1,0]
	v_pk_mul_f32 v[28:29], v[28:29], v[142:143] op_sel_hi:[1,0]
	v_pk_mul_f32 v[30:31], v[30:31], v[142:143] op_sel_hi:[1,0]
	v_mul_f32_e32 v168, 0xbfb8aa3b, v64
	v_mul_f32_e32 v169, 0xbfb8aa3b, v65
	v_mul_f32_e32 v170, 0xbfb8aa3b, v66
	v_mul_f32_e32 v171, 0xbfb8aa3b, v67
	v_exp_f32_e32 v168, v168
	v_exp_f32_e32 v169, v169
	v_exp_f32_e32 v170, v170
	v_exp_f32_e32 v171, v171
	v_add_f32_e32 v168, 1.0, v168
	v_add_f32_e32 v169, 1.0, v169
	v_add_f32_e32 v170, 1.0, v170
	v_add_f32_e32 v171, 1.0, v171
	v_rcp_f32_e32 v168, v168
	v_rcp_f32_e32 v169, v169
	v_rcp_f32_e32 v170, v170
	v_rcp_f32_e32 v171, v171
	v_pk_mul_f32 v[64:65], v[64:65], v[168:169]
	v_pk_mul_f32 v[66:67], v[66:67], v[170:171]
	v_mul_f32_e32 v168, 0xbfb8aa3b, v60
	v_mul_f32_e32 v169, 0xbfb8aa3b, v61
	v_mul_f32_e32 v170, 0xbfb8aa3b, v62
	v_mul_f32_e32 v171, 0xbfb8aa3b, v63
	v_exp_f32_e32 v168, v168
	v_exp_f32_e32 v169, v169
	v_exp_f32_e32 v170, v170
	v_exp_f32_e32 v171, v171
	v_add_f32_e32 v168, 1.0, v168
	v_add_f32_e32 v169, 1.0, v169
	v_add_f32_e32 v170, 1.0, v170
	v_add_f32_e32 v171, 1.0, v171
	v_rcp_f32_e32 v168, v168
	v_rcp_f32_e32 v169, v169
	v_rcp_f32_e32 v170, v170
	v_rcp_f32_e32 v171, v171
	v_pk_mul_f32 v[60:61], v[60:61], v[168:169]
	v_pk_mul_f32 v[62:63], v[62:63], v[170:171]
	v_mul_f32_e32 v168, 0xbfb8aa3b, v32
	v_mul_f32_e32 v169, 0xbfb8aa3b, v33
	v_mul_f32_e32 v170, 0xbfb8aa3b, v34
	v_mul_f32_e32 v171, 0xbfb8aa3b, v35
	v_exp_f32_e32 v168, v168
	v_exp_f32_e32 v169, v169
	v_exp_f32_e32 v170, v170
	v_exp_f32_e32 v171, v171
	v_add_f32_e32 v168, 1.0, v168
	v_add_f32_e32 v169, 1.0, v169
	v_add_f32_e32 v170, 1.0, v170
	v_add_f32_e32 v171, 1.0, v171
	v_rcp_f32_e32 v168, v168
	v_rcp_f32_e32 v169, v169
	v_rcp_f32_e32 v170, v170
	v_rcp_f32_e32 v171, v171
	v_pk_mul_f32 v[32:33], v[32:33], v[168:169]
	v_pk_mul_f32 v[34:35], v[34:35], v[170:171]
	v_mul_f32_e32 v168, 0xbfb8aa3b, v28
	v_mul_f32_e32 v169, 0xbfb8aa3b, v29
	v_mul_f32_e32 v170, 0xbfb8aa3b, v30
	v_mul_f32_e32 v171, 0xbfb8aa3b, v31
	v_exp_f32_e32 v168, v168
	v_exp_f32_e32 v169, v169
	v_exp_f32_e32 v170, v170
	v_exp_f32_e32 v171, v171
	v_add_f32_e32 v168, 1.0, v168
	v_add_f32_e32 v169, 1.0, v169
	v_add_f32_e32 v170, 1.0, v170
	v_add_f32_e32 v171, 1.0, v171
	v_rcp_f32_e32 v168, v168
	v_rcp_f32_e32 v169, v169
	v_rcp_f32_e32 v170, v170
	v_rcp_f32_e32 v171, v171
	v_pk_mul_f32 v[28:29], v[28:29], v[168:169]
	v_pk_mul_f32 v[30:31], v[30:31], v[170:171]
	v_cvt_pk_f16_f32 v152, v64, v65
	v_cvt_pk_f16_f32 v153, v66, v67
	v_cvt_pk_f16_f32 v154, v60, v61
	v_cvt_pk_f16_f32 v155, v62, v63
	global_store_dwordx4 v133, v[152:155], s[6:7] nt
	v_cvt_pk_f16_f32 v156, v32, v33
	v_cvt_pk_f16_f32 v157, v34, v35
	v_cvt_pk_f16_f32 v158, v28, v29
	v_cvt_pk_f16_f32 v159, v30, v31
	global_store_dwordx4 v133, v[156:159], s[6:7] offset:2048 nt
	s_add_u32 s6, s4, 0x20100
	s_addc_u32 s7, s5, 0
	v_pk_mul_f32 v[56:57], v[56:57], v[144:145] op_sel_hi:[1,0]
	v_pk_mul_f32 v[58:59], v[58:59], v[144:145] op_sel_hi:[1,0]
	v_pk_mul_f32 v[52:53], v[52:53], v[144:145] op_sel_hi:[1,0]
	v_pk_mul_f32 v[54:55], v[54:55], v[144:145] op_sel_hi:[1,0]
	v_pk_mul_f32 v[24:25], v[24:25], v[144:145] op_sel_hi:[1,0]
	v_pk_mul_f32 v[26:27], v[26:27], v[144:145] op_sel_hi:[1,0]
	v_pk_mul_f32 v[20:21], v[20:21], v[144:145] op_sel_hi:[1,0]
	v_pk_mul_f32 v[22:23], v[22:23], v[144:145] op_sel_hi:[1,0]
	v_mul_f32_e32 v168, 0xbfb8aa3b, v56
	v_mul_f32_e32 v169, 0xbfb8aa3b, v57
	v_mul_f32_e32 v170, 0xbfb8aa3b, v58
	v_mul_f32_e32 v171, 0xbfb8aa3b, v59
	v_exp_f32_e32 v168, v168
	v_exp_f32_e32 v169, v169
	v_exp_f32_e32 v170, v170
	v_exp_f32_e32 v171, v171
	v_add_f32_e32 v168, 1.0, v168
	v_add_f32_e32 v169, 1.0, v169
	v_add_f32_e32 v170, 1.0, v170
	v_add_f32_e32 v171, 1.0, v171
	v_rcp_f32_e32 v168, v168
	v_rcp_f32_e32 v169, v169
	v_rcp_f32_e32 v170, v170
	v_rcp_f32_e32 v171, v171
	v_pk_mul_f32 v[56:57], v[56:57], v[168:169]
	v_pk_mul_f32 v[58:59], v[58:59], v[170:171]
	v_mul_f32_e32 v168, 0xbfb8aa3b, v52
	v_mul_f32_e32 v169, 0xbfb8aa3b, v53
	v_mul_f32_e32 v170, 0xbfb8aa3b, v54
	v_mul_f32_e32 v171, 0xbfb8aa3b, v55
	v_exp_f32_e32 v168, v168
	v_exp_f32_e32 v169, v169
	v_exp_f32_e32 v170, v170
	v_exp_f32_e32 v171, v171
	v_add_f32_e32 v168, 1.0, v168
	v_add_f32_e32 v169, 1.0, v169
	v_add_f32_e32 v170, 1.0, v170
	v_add_f32_e32 v171, 1.0, v171
	v_rcp_f32_e32 v168, v168
	v_rcp_f32_e32 v169, v169
	v_rcp_f32_e32 v170, v170
	v_rcp_f32_e32 v171, v171
	v_pk_mul_f32 v[52:53], v[52:53], v[168:169]
	v_pk_mul_f32 v[54:55], v[54:55], v[170:171]
	v_mul_f32_e32 v168, 0xbfb8aa3b, v24
	v_mul_f32_e32 v169, 0xbfb8aa3b, v25
	v_mul_f32_e32 v170, 0xbfb8aa3b, v26
	v_mul_f32_e32 v171, 0xbfb8aa3b, v27
	v_exp_f32_e32 v168, v168
	v_exp_f32_e32 v169, v169
	v_exp_f32_e32 v170, v170
	v_exp_f32_e32 v171, v171
	v_add_f32_e32 v168, 1.0, v168
	v_add_f32_e32 v169, 1.0, v169
	v_add_f32_e32 v170, 1.0, v170
	v_add_f32_e32 v171, 1.0, v171
	v_rcp_f32_e32 v168, v168
	v_rcp_f32_e32 v169, v169
	v_rcp_f32_e32 v170, v170
	v_rcp_f32_e32 v171, v171
	v_pk_mul_f32 v[24:25], v[24:25], v[168:169]
	v_pk_mul_f32 v[26:27], v[26:27], v[170:171]
	v_mul_f32_e32 v168, 0xbfb8aa3b, v20
	v_mul_f32_e32 v169, 0xbfb8aa3b, v21
	v_mul_f32_e32 v170, 0xbfb8aa3b, v22
	v_mul_f32_e32 v171, 0xbfb8aa3b, v23
	v_exp_f32_e32 v168, v168
	v_exp_f32_e32 v169, v169
	v_exp_f32_e32 v170, v170
; #define GAS __attribute__((address_space(1)))
; __host__ __device__ __forceinline__ size_t bl512(size_t row, int col) { return ((row >> 5) * 64 + (size_t)(col >> 3)) * 256 + (row & 31) * 8 + (col & 7); }
; __device__ __forceinline__ float silu_f(float v) { return v * __builtin_amdgcn_rcpf(1.0f + __builtin_amdgcn_exp2f(-v * LOG2E)); }
;     __device__ __forceinline__ void operator()(const f32x4 (&acc)[2][2][4][2], const Unit& u, int wr, int wc, int fr, int fq) const {
;     ...
;                 } else if (sec == 3 || sec == 7) {
; #pragma unroll
;                     for (int bj = 0; bj < 2; ++bj)
; #pragma unroll
;                         for (int n = 0; n < 2; ++n)
; #pragma unroll
;                             for (int e = 0; e < 4; ++e) v[bj][n][e] = silu_f(v[bj][n][e]);
;                 }
;                 GAS f16* rowp = isqg ? QG + (size_t)dsec * QG_SEC + bl512((size_t)row, cs) : KV + (size_t)row * KVW + dsec * 512 + cs;
; #pragma unroll
;                 for (int bj = 0; bj < 2; ++bj) {
;                     u32x4 w; w.x = pkh(v[bj][0][0], v[bj][0][1]); w.y = pkh(v[bj][0][2], v[bj][0][3]); w.z = pkh(v[bj][1][0], v[bj][1][1]); w.w = pkh(v[bj][1][2], v[bj][1][3]);
;                     *(GAS u32x4*)(rowp + bjstep * bj) = w;
;                 }
	v_exp_f32_e32 v171, v171
	v_add_f32_e32 v168, 1.0, v168
	v_add_f32_e32 v169, 1.0, v169
	v_add_f32_e32 v170, 1.0, v170
	v_add_f32_e32 v171, 1.0, v171
	v_rcp_f32_e32 v168, v168
	v_rcp_f32_e32 v169, v169
	v_rcp_f32_e32 v170, v170
	v_rcp_f32_e32 v171, v171
	v_pk_mul_f32 v[20:21], v[20:21], v[168:169]
	v_pk_mul_f32 v[22:23], v[22:23], v[170:171]
	v_cvt_pk_f16_f32 v160, v56, v57
	v_cvt_pk_f16_f32 v161, v58, v59
	v_cvt_pk_f16_f32 v162, v52, v53
	v_cvt_pk_f16_f32 v163, v54, v55
	global_store_dwordx4 v133, v[160:163], s[6:7] nt
	v_cvt_pk_f16_f32 v164, v24, v25
	v_cvt_pk_f16_f32 v165, v26, v27
	v_cvt_pk_f16_f32 v166, v20, v21
	v_cvt_pk_f16_f32 v167, v22, v23
	global_store_dwordx4 v133, v[164:167], s[6:7] offset:2048 nt
	s_add_u32 s6, s4, 0x28000
	s_addc_u32 s7, s5, 0
	v_pk_mul_f32 v[48:49], v[48:49], v[146:147] op_sel_hi:[1,0]
	v_pk_mul_f32 v[50:51], v[50:51], v[146:147] op_sel_hi:[1,0]
	v_pk_mul_f32 v[44:45], v[44:45], v[146:147] op_sel_hi:[1,0]
	v_pk_mul_f32 v[46:47], v[46:47], v[146:147] op_sel_hi:[1,0]
	v_pk_mul_f32 v[16:17], v[16:17], v[146:147] op_sel_hi:[1,0]
	v_pk_mul_f32 v[18:19], v[18:19], v[146:147] op_sel_hi:[1,0]
	v_pk_mul_f32 v[12:13], v[12:13], v[146:147] op_sel_hi:[1,0]
	v_pk_mul_f32 v[14:15], v[14:15], v[146:147] op_sel_hi:[1,0]
	v_mul_f32_e32 v168, 0xbfb8aa3b, v48
	v_mul_f32_e32 v169, 0xbfb8aa3b, v49
	v_mul_f32_e32 v170, 0xbfb8aa3b, v50
	v_mul_f32_e32 v171, 0xbfb8aa3b, v51
	v_exp_f32_e32 v168, v168
	v_exp_f32_e32 v169, v169
	v_exp_f32_e32 v170, v170
	v_exp_f32_e32 v171, v171
	v_add_f32_e32 v168, 1.0, v168
	v_add_f32_e32 v169, 1.0, v169
	v_add_f32_e32 v170, 1.0, v170
	v_add_f32_e32 v171, 1.0, v171
	v_rcp_f32_e32 v168, v168
	v_rcp_f32_e32 v169, v169
	v_rcp_f32_e32 v170, v170
	v_rcp_f32_e32 v171, v171
	v_pk_mul_f32 v[48:49], v[48:49], v[168:169]
	v_pk_mul_f32 v[50:51], v[50:51], v[170:171]
	v_mul_f32_e32 v168, 0xbfb8aa3b, v44
	v_mul_f32_e32 v169, 0xbfb8aa3b, v45
	v_mul_f32_e32 v170, 0xbfb8aa3b, v46
	v_mul_f32_e32 v171, 0xbfb8aa3b, v47
	v_exp_f32_e32 v168, v168
	v_exp_f32_e32 v169, v169
	v_exp_f32_e32 v170, v170
	v_exp_f32_e32 v171, v171
	v_add_f32_e32 v168, 1.0, v168
	v_add_f32_e32 v169, 1.0, v169
	v_add_f32_e32 v170, 1.0, v170
	v_add_f32_e32 v171, 1.0, v171
	v_rcp_f32_e32 v168, v168
	v_rcp_f32_e32 v169, v169
	v_rcp_f32_e32 v170, v170
	v_rcp_f32_e32 v171, v171
	v_pk_mul_f32 v[44:45], v[44:45], v[168:169]
	v_pk_mul_f32 v[46:47], v[46:47], v[170:171]
	v_mul_f32_e32 v168, 0xbfb8aa3b, v16
	v_mul_f32_e32 v169, 0xbfb8aa3b, v17
	v_mul_f32_e32 v170, 0xbfb8aa3b, v18
	v_mul_f32_e32 v171, 0xbfb8aa3b, v19
	v_exp_f32_e32 v168, v168
	v_exp_f32_e32 v169, v169
	v_exp_f32_e32 v170, v170
	v_exp_f32_e32 v171, v171
	v_add_f32_e32 v168, 1.0, v168
	v_add_f32_e32 v169, 1.0, v169
	v_add_f32_e32 v170, 1.0, v170
	v_add_f32_e32 v171, 1.0, v171
	v_rcp_f32_e32 v168, v168
	v_rcp_f32_e32 v169, v169
	v_rcp_f32_e32 v170, v170
	v_rcp_f32_e32 v171, v171
	v_pk_mul_f32 v[16:17], v[16:17], v[168:169]
	v_pk_mul_f32 v[18:19], v[18:19], v[170:171]
	v_mul_f32_e32 v168, 0xbfb8aa3b, v12
	v_mul_f32_e32 v169, 0xbfb8aa3b, v13
	v_mul_f32_e32 v170, 0xbfb8aa3b, v14
	v_mul_f32_e32 v171, 0xbfb8aa3b, v15
	v_exp_f32_e32 v168, v168
	v_exp_f32_e32 v169, v169
	v_exp_f32_e32 v170, v170
	v_exp_f32_e32 v171, v171
	v_add_f32_e32 v168, 1.0, v168
	v_add_f32_e32 v169, 1.0, v169
	v_add_f32_e32 v170, 1.0, v170
	v_add_f32_e32 v171, 1.0, v171
	v_rcp_f32_e32 v168, v168
	v_rcp_f32_e32 v169, v169
	v_rcp_f32_e32 v170, v170
	v_rcp_f32_e32 v171, v171
	v_pk_mul_f32 v[12:13], v[12:13], v[168:169]
	v_pk_mul_f32 v[14:15], v[14:15], v[170:171]
	v_cvt_pk_f16_f32 v152, v48, v49
	v_cvt_pk_f16_f32 v153, v50, v51
	v_cvt_pk_f16_f32 v154, v44, v45
	v_cvt_pk_f16_f32 v155, v46, v47
	global_store_dwordx4 v133, v[152:155], s[6:7] nt
	v_cvt_pk_f16_f32 v156, v16, v17
	v_cvt_pk_f16_f32 v157, v18, v19
	v_cvt_pk_f16_f32 v158, v12, v13
	v_cvt_pk_f16_f32 v159, v14, v15
	global_store_dwordx4 v133, v[156:159], s[6:7] offset:2048 nt
	s_add_u32 s6, s4, 0x28100
	s_addc_u32 s7, s5, 0
	v_pk_mul_f32 v[40:41], v[40:41], v[148:149] op_sel_hi:[1,0]
	v_pk_mul_f32 v[42:43], v[42:43], v[148:149] op_sel_hi:[1,0]
	v_pk_mul_f32 v[36:37], v[36:37], v[148:149] op_sel_hi:[1,0]
	v_pk_mul_f32 v[38:39], v[38:39], v[148:149] op_sel_hi:[1,0]
	v_pk_mul_f32 v[8:9], v[8:9], v[148:149] op_sel_hi:[1,0]
	v_pk_mul_f32 v[10:11], v[10:11], v[148:149] op_sel_hi:[1,0]
	v_pk_mul_f32 v[4:5], v[4:5], v[148:149] op_sel_hi:[1,0]
	v_pk_mul_f32 v[6:7], v[6:7], v[148:149] op_sel_hi:[1,0]
	v_mul_f32_e32 v168, 0xbfb8aa3b, v40
	v_mul_f32_e32 v169, 0xbfb8aa3b, v41
	v_mul_f32_e32 v170, 0xbfb8aa3b, v42
	v_mul_f32_e32 v171, 0xbfb8aa3b, v43
	v_exp_f32_e32 v168, v168
	v_exp_f32_e32 v169, v169
	v_exp_f32_e32 v170, v170
	v_exp_f32_e32 v171, v171
	v_add_f32_e32 v168, 1.0, v168
	v_add_f32_e32 v169, 1.0, v169
	v_add_f32_e32 v170, 1.0, v170
	v_add_f32_e32 v171, 1.0, v171
	v_rcp_f32_e32 v168, v168
	v_rcp_f32_e32 v169, v169
	v_rcp_f32_e32 v170, v170
	v_rcp_f32_e32 v171, v171
	v_pk_mul_f32 v[40:41], v[40:41], v[168:169]
	v_pk_mul_f32 v[42:43], v[42:43], v[170:171]
	v_mul_f32_e32 v168, 0xbfb8aa3b, v36
	v_mul_f32_e32 v169, 0xbfb8aa3b, v37
	v_mul_f32_e32 v170, 0xbfb8aa3b, v38
	v_mul_f32_e32 v171, 0xbfb8aa3b, v39
	v_exp_f32_e32 v168, v168
	v_exp_f32_e32 v169, v169
	v_exp_f32_e32 v170, v170
	v_exp_f32_e32 v171, v171
	v_add_f32_e32 v168, 1.0, v168
	v_add_f32_e32 v169, 1.0, v169
	v_add_f32_e32 v170, 1.0, v170
	v_add_f32_e32 v171, 1.0, v171
	v_rcp_f32_e32 v168, v168
	v_rcp_f32_e32 v169, v169
	v_rcp_f32_e32 v170, v170
	v_rcp_f32_e32 v171, v171
	v_pk_mul_f32 v[36:37], v[36:37], v[168:169]
	v_pk_mul_f32 v[38:39], v[38:39], v[170:171]
	v_mul_f32_e32 v168, 0xbfb8aa3b, v8
	v_mul_f32_e32 v169, 0xbfb8aa3b, v9
; #define LAS __attribute__((address_space(3)))
; #define GAS __attribute__((address_space(1)))
;     __device__ __forceinline__ void operator()(const f32x4 (&acc)[2][2][4][2], const Unit& u, int wr, int wc, int fr, int fq) const {
;     ...
;         if (sec == 4 || sec == 5) {
;             const GAS float* g = (sec == 4) ? gq : gk;
; #pragma unroll
;             for (int bj = 0; bj < 2; ++bj)
; #pragma unroll
;                 for (int n = 0; n < 2; ++n) gain[bj][n] = *(const GAS f32x4*)(g + 32 * bj + 8 * fq + 4 * n);
;         }
;         const LAS int* tags = (const LAS int*)(rsc + 2048);
;         const int slot = (tags[0] == u.pm) ? 0 : (tags[1] == u.pm) ? 1 : -1;
;         const LAS float* rtab = (const LAS float*)rsc + (slot > 0 ? 256 : 0) + wr * 64 + fr;
; #pragma unroll
;         for (int ai = 0; ai < 2; ++ai)
; #pragma unroll
;             for (int m = 0; m < 4; ++m) {
;                 const int row = row0 + ai * HALF + m * 16;
;                 float rs;
;                 if (slot >= 0) rs = rtab[ai * HALF + m * 16];
;                 else {
;                     const f32x4 pv = *(const GAS f32x4*)(part + (size_t)row * 16 + fq * 4);
;                     float s = (pv[0] + pv[1]) + (pv[2] + pv[3]);
;                     s = row4_sum(s);
;                     rs = __builtin_amdgcn_rsqf(s * (1.0f / DM) + RMS_EPS);
;                 }
;                 f32x4 v[2][2];
; #pragma unroll
;                 for (int bj = 0; bj < 2; ++bj)
; #pragma unroll
;                     for (int n = 0; n < 2; ++n) v[bj][n] = acc[ai][bj][m][n] * rs;
;                 if (sec == 4 || sec == 5) {
;                     float ss = 0.f;
; #pragma unroll
;                     for (int bj = 0; bj < 2; ++bj)
; #pragma unroll
;                         for (int n = 0; n < 2; ++n) { const f32x4 x = v[bj][n]; ss += (x[0] * x[0] + x[1] * x[1]) + (x[2] * x[2] + x[3] * x[3]); }
;                     ss = row4_sum(ss);
;                     float rn = __builtin_amdgcn_rsqf(ss * (1.0f / 64.0f) + RMS_EPS);
;                     if (sec == 4) rn *= QS;
; #pragma unroll
;                     for (int bj = 0; bj < 2; ++bj)
; #pragma unroll
;                         for (int n = 0; n < 2; ++n) v[bj][n] = v[bj][n] * rn * gain[bj][n];
	v_mul_f32_e32 v170, 0xbfb8aa3b, v10
	v_mul_f32_e32 v171, 0xbfb8aa3b, v11
	v_exp_f32_e32 v168, v168
	v_exp_f32_e32 v169, v169
	v_exp_f32_e32 v170, v170
	v_exp_f32_e32 v171, v171
	v_add_f32_e32 v168, 1.0, v168
	v_add_f32_e32 v169, 1.0, v169
	v_add_f32_e32 v170, 1.0, v170
	v_add_f32_e32 v171, 1.0, v171
	v_rcp_f32_e32 v168, v168
	v_rcp_f32_e32 v169, v169
	v_rcp_f32_e32 v170, v170
	v_rcp_f32_e32 v171, v171
	v_pk_mul_f32 v[8:9], v[8:9], v[168:169]
	v_pk_mul_f32 v[10:11], v[10:11], v[170:171]
	v_mul_f32_e32 v168, 0xbfb8aa3b, v4
	v_mul_f32_e32 v169, 0xbfb8aa3b, v5
	v_mul_f32_e32 v170, 0xbfb8aa3b, v6
	v_mul_f32_e32 v171, 0xbfb8aa3b, v7
	v_exp_f32_e32 v168, v168
	v_exp_f32_e32 v169, v169
	v_exp_f32_e32 v170, v170
	v_exp_f32_e32 v171, v171
	v_add_f32_e32 v168, 1.0, v168
	v_add_f32_e32 v169, 1.0, v169
	v_add_f32_e32 v170, 1.0, v170
	v_add_f32_e32 v171, 1.0, v171
	v_rcp_f32_e32 v168, v168
	v_rcp_f32_e32 v169, v169
	v_rcp_f32_e32 v170, v170
	v_rcp_f32_e32 v171, v171
	v_pk_mul_f32 v[4:5], v[4:5], v[168:169]
	v_pk_mul_f32 v[6:7], v[6:7], v[170:171]
	v_cvt_pk_f16_f32 v160, v40, v41
	v_cvt_pk_f16_f32 v161, v42, v43
	v_cvt_pk_f16_f32 v162, v36, v37
	v_cvt_pk_f16_f32 v163, v38, v39
	global_store_dwordx4 v133, v[160:163], s[6:7] nt
	v_cvt_pk_f16_f32 v164, v8, v9
	v_cvt_pk_f16_f32 v165, v10, v11
	v_cvt_pk_f16_f32 v166, v4, v5
	v_cvt_pk_f16_f32 v167, v6, v7
	global_store_dwordx4 v133, v[164:167], s[6:7] offset:2048 nt
	s_branch .Lepi_done_g1
.Lepi_qn:
	s_and_b32 s0, s70, 1
	s_lshl_b32 s0, s0, 10
	v_add_u32_e32 v132, s0, v219
	ds_read_b32 v134, v132
	ds_read_b32 v136, v132 offset:64
	ds_read_b32 v138, v132 offset:128
	ds_read_b32 v140, v132 offset:192
	ds_read_b32 v142, v132 offset:512
	ds_read_b32 v144, v132 offset:576
	ds_read_b32 v146, v132 offset:640
	ds_read_b32 v148, v132 offset:704
	s_lshr_b32 s0, s69, 2
	s_and_b32 s1, s69, 1
	v_lshrrev_b32_e32 v2, 6, v187
	v_lshrrev_b32_e32 v133, 3, v220
	v_lshl_add_u32 v133, v2, 7, v133
	v_and_b32_e32 v2, 15, v187
	v_lshlrev_b32_e32 v133, 8, v133
	v_lshl_add_u32 v133, v2, 3, v133
	v_lshlrev_b32_e32 v133, 1, v133
	s_lshl_b32 s0, s0, 25
	s_lshl_b32 s1, s1, 14
	s_add_u32 s0, s0, s1
	s_lshl_b32 s1, s68, 18
	s_add_u32 s0, s0, s1
	s_add_u32 s4, s82, s0
	s_addc_u32 s5, s83, 0
	v_readlane_b32 s10, v252, 17
	v_readlane_b32 s11, v252, 18
	s_lshl_b32 s0, s22, 2
	s_nop 0
	s_add_u32 s10, s10, s0
	s_addc_u32 s11, s11, 0
	s_nop 3
	global_load_dwordx4 v[176:179], v222, s[10:11]
	global_load_dwordx4 v[206:209], v222, s[10:11] offset:16
	global_load_dwordx4 v[224:227], v222, s[10:11] offset:128
	global_load_dwordx4 v[228:231], v222, s[10:11] offset:144
	s_waitcnt vmcnt(0)
	s_waitcnt lgkmcnt(0)
	s_mov_b32 s6, s4
	s_mov_b32 s7, s5
	v_pk_mul_f32 v[128:129], v[128:129], v[134:135] op_sel_hi:[1,0]
	v_pk_mul_f32 v[130:131], v[130:131], v[134:135] op_sel_hi:[1,0]
	v_pk_mul_f32 v[124:125], v[124:125], v[134:135] op_sel_hi:[1,0]
	v_pk_mul_f32 v[126:127], v[126:127], v[134:135] op_sel_hi:[1,0]
	v_pk_mul_f32 v[96:97], v[96:97], v[134:135] op_sel_hi:[1,0]
	v_pk_mul_f32 v[98:99], v[98:99], v[134:135] op_sel_hi:[1,0]
	v_pk_mul_f32 v[92:93], v[92:93], v[134:135] op_sel_hi:[1,0]
	v_pk_mul_f32 v[94:95], v[94:95], v[134:135] op_sel_hi:[1,0]
	v_mul_f32_e32 v2, v128, v128
	v_mul_f32_e32 v150, v129, v129
	v_fmac_f32_e32 v2, v130, v130
	v_fmac_f32_e32 v150, v131, v131
	v_fmac_f32_e32 v2, v124, v124
	v_fmac_f32_e32 v150, v125, v125
	v_fmac_f32_e32 v2, v126, v126
	v_fmac_f32_e32 v150, v127, v127
	v_fmac_f32_e32 v2, v96, v96
	v_fmac_f32_e32 v150, v97, v97
	v_fmac_f32_e32 v2, v98, v98
	v_fmac_f32_e32 v150, v99, v99
	v_fmac_f32_e32 v2, v92, v92
	v_fmac_f32_e32 v150, v93, v93
	v_fmac_f32_e32 v2, v94, v94
	v_fmac_f32_e32 v150, v95, v95
	v_add_f32_e32 v2, v2, v150
	v_mov_b32_e32 v150, v2
	s_nop 1
	v_permlane16_swap_b32_e32 v2, v150
	v_add_f32_e32 v2, v2, v150
	v_mov_b32_e32 v150, v2
	s_nop 1
	v_permlane32_swap_b32_e32 v2, v150
	v_add_f32_e32 v2, v2, v150
	v_fmamk_f32 v2, v2, 0x3c800000, v211
	v_rsq_f32_e32 v2, v2
	s_nop 0
	v_mul_f32_e32 v2, s78, v2
	v_pk_mul_f32 v[128:129], v[128:129], v[2:3] op_sel_hi:[1,0]
	v_pk_mul_f32 v[130:131], v[130:131], v[2:3] op_sel_hi:[1,0]
	v_pk_mul_f32 v[124:125], v[124:125], v[2:3] op_sel_hi:[1,0]
	v_pk_mul_f32 v[126:127], v[126:127], v[2:3] op_sel_hi:[1,0]
	v_pk_mul_f32 v[96:97], v[96:97], v[2:3] op_sel_hi:[1,0]
	v_pk_mul_f32 v[98:99], v[98:99], v[2:3] op_sel_hi:[1,0]
	v_pk_mul_f32 v[92:93], v[92:93], v[2:3] op_sel_hi:[1,0]
	v_pk_mul_f32 v[94:95], v[94:95], v[2:3] op_sel_hi:[1,0]
	v_pk_mul_f32 v[128:129], v[128:129], v[176:177]
	v_pk_mul_f32 v[130:131], v[130:131], v[178:179]
	v_pk_mul_f32 v[124:125], v[124:125], v[206:207]
	v_pk_mul_f32 v[126:127], v[126:127], v[208:209]
	v_pk_mul_f32 v[96:97], v[96:97], v[224:225]
	v_pk_mul_f32 v[98:99], v[98:99], v[226:227]
	v_pk_mul_f32 v[92:93], v[92:93], v[228:229]
	v_pk_mul_f32 v[94:95], v[94:95], v[230:231]
	v_cvt_pk_f16_f32 v152, v128, v129
	v_cvt_pk_f16_f32 v153, v130, v131
	v_cvt_pk_f16_f32 v154, v124, v125
	v_cvt_pk_f16_f32 v155, v126, v127
	global_store_dwordx4 v133, v[152:155], s[6:7] nt
	v_cvt_pk_f16_f32 v156, v96, v97
	v_cvt_pk_f16_f32 v157, v98, v99
	v_cvt_pk_f16_f32 v158, v92, v93
	v_cvt_pk_f16_f32 v159, v94, v95
	global_store_dwordx4 v133, v[156:159], s[6:7] offset:2048 nt
	s_add_u32 s6, s4, 0x100
	s_addc_u32 s7, s5, 0
	v_pk_mul_f32 v[120:121], v[120:121], v[136:137] op_sel_hi:[1,0]
	v_pk_mul_f32 v[122:123], v[122:123], v[136:137] op_sel_hi:[1,0]
	v_pk_mul_f32 v[116:117], v[116:117], v[136:137] op_sel_hi:[1,0]
	v_pk_mul_f32 v[118:119], v[118:119], v[136:137] op_sel_hi:[1,0]
	v_pk_mul_f32 v[88:89], v[88:89], v[136:137] op_sel_hi:[1,0]
	v_pk_mul_f32 v[90:91], v[90:91], v[136:137] op_sel_hi:[1,0]
; #define GAS __attribute__((address_space(1)))
; __host__ __device__ __forceinline__ size_t bl512(size_t row, int col) { return ((row >> 5) * 64 + (size_t)(col >> 3)) * 256 + (row & 31) * 8 + (col & 7); }
; __device__ __forceinline__ float silu_f(float v) { return v * __builtin_amdgcn_rcpf(1.0f + __builtin_amdgcn_exp2f(-v * LOG2E)); }
;     __device__ __forceinline__ void operator()(const f32x4 (&acc)[2][2][4][2], const Unit& u, int wr, int wc, int fr, int fq) const {
;     ...
;                 if (sec == 4 || sec == 5) {
;                     float ss = 0.f;
; #pragma unroll
;                     for (int bj = 0; bj < 2; ++bj)
; #pragma unroll
;                         for (int n = 0; n < 2; ++n) { const f32x4 x = v[bj][n]; ss += (x[0] * x[0] + x[1] * x[1]) + (x[2] * x[2] + x[3] * x[3]); }
;                     ss = row4_sum(ss);
;                     float rn = __builtin_amdgcn_rsqf(ss * (1.0f / 64.0f) + RMS_EPS);
;                     if (sec == 4) rn *= QS;
; #pragma unroll
;                     for (int bj = 0; bj < 2; ++bj)
; #pragma unroll
;                         for (int n = 0; n < 2; ++n) v[bj][n] = v[bj][n] * rn * gain[bj][n];
;                 } else if (sec == 0) {
; #pragma unroll
;                     for (int bj = 0; bj < 2; ++bj)
; #pragma unroll
;                         for (int n = 0; n < 2; ++n) v[bj][n] = v[bj][n] * QS;
;                 } else if (sec == 3 || sec == 7) {
; #pragma unroll
;                     for (int bj = 0; bj < 2; ++bj)
; #pragma unroll
;                         for (int n = 0; n < 2; ++n)
; #pragma unroll
;                             for (int e = 0; e < 4; ++e) v[bj][n][e] = silu_f(v[bj][n][e]);
;                 }
;                 GAS f16* rowp = isqg ? QG + (size_t)dsec * QG_SEC + bl512((size_t)row, cs) : KV + (size_t)row * KVW + dsec * 512 + cs;
; #pragma unroll
;                 for (int bj = 0; bj < 2; ++bj) {
;                     u32x4 w; w.x = pkh(v[bj][0][0], v[bj][0][1]); w.y = pkh(v[bj][0][2], v[bj][0][3]); w.z = pkh(v[bj][1][0], v[bj][1][1]); w.w = pkh(v[bj][1][2], v[bj][1][3]);
;                     *(GAS u32x4*)(rowp + bjstep * bj) = w;
;                 }
	v_pk_mul_f32 v[84:85], v[84:85], v[136:137] op_sel_hi:[1,0]
	v_pk_mul_f32 v[86:87], v[86:87], v[136:137] op_sel_hi:[1,0]
	v_mul_f32_e32 v2, v120, v120
	v_mul_f32_e32 v150, v121, v121
	v_fmac_f32_e32 v2, v122, v122
	v_fmac_f32_e32 v150, v123, v123
	v_fmac_f32_e32 v2, v116, v116
	v_fmac_f32_e32 v150, v117, v117
	v_fmac_f32_e32 v2, v118, v118
	v_fmac_f32_e32 v150, v119, v119
	v_fmac_f32_e32 v2, v88, v88
	v_fmac_f32_e32 v150, v89, v89
	v_fmac_f32_e32 v2, v90, v90
	v_fmac_f32_e32 v150, v91, v91
	v_fmac_f32_e32 v2, v84, v84
	v_fmac_f32_e32 v150, v85, v85
	v_fmac_f32_e32 v2, v86, v86
	v_fmac_f32_e32 v150, v87, v87
	v_add_f32_e32 v2, v2, v150
	v_mov_b32_e32 v150, v2
	s_nop 1
	v_permlane16_swap_b32_e32 v2, v150
	v_add_f32_e32 v2, v2, v150
	v_mov_b32_e32 v150, v2
	s_nop 1
	v_permlane32_swap_b32_e32 v2, v150
	v_add_f32_e32 v2, v2, v150
	v_fmamk_f32 v2, v2, 0x3c800000, v211
	v_rsq_f32_e32 v2, v2
	s_nop 0
	v_mul_f32_e32 v2, s78, v2
	v_pk_mul_f32 v[120:121], v[120:121], v[2:3] op_sel_hi:[1,0]
	v_pk_mul_f32 v[122:123], v[122:123], v[2:3] op_sel_hi:[1,0]
	v_pk_mul_f32 v[116:117], v[116:117], v[2:3] op_sel_hi:[1,0]
	v_pk_mul_f32 v[118:119], v[118:119], v[2:3] op_sel_hi:[1,0]
	v_pk_mul_f32 v[88:89], v[88:89], v[2:3] op_sel_hi:[1,0]
	v_pk_mul_f32 v[90:91], v[90:91], v[2:3] op_sel_hi:[1,0]
	v_pk_mul_f32 v[84:85], v[84:85], v[2:3] op_sel_hi:[1,0]
	v_pk_mul_f32 v[86:87], v[86:87], v[2:3] op_sel_hi:[1,0]
	v_pk_mul_f32 v[120:121], v[120:121], v[176:177]
	v_pk_mul_f32 v[122:123], v[122:123], v[178:179]
	v_pk_mul_f32 v[116:117], v[116:117], v[206:207]
	v_pk_mul_f32 v[118:119], v[118:119], v[208:209]
	v_pk_mul_f32 v[88:89], v[88:89], v[224:225]
	v_pk_mul_f32 v[90:91], v[90:91], v[226:227]
	v_pk_mul_f32 v[84:85], v[84:85], v[228:229]
	v_pk_mul_f32 v[86:87], v[86:87], v[230:231]
	v_cvt_pk_f16_f32 v160, v120, v121
	v_cvt_pk_f16_f32 v161, v122, v123
	v_cvt_pk_f16_f32 v162, v116, v117
	v_cvt_pk_f16_f32 v163, v118, v119
	global_store_dwordx4 v133, v[160:163], s[6:7] nt
	v_cvt_pk_f16_f32 v164, v88, v89
	v_cvt_pk_f16_f32 v165, v90, v91
	v_cvt_pk_f16_f32 v166, v84, v85
	v_cvt_pk_f16_f32 v167, v86, v87
	global_store_dwordx4 v133, v[164:167], s[6:7] offset:2048 nt
	s_add_u32 s6, s4, 0x8000
	s_addc_u32 s7, s5, 0
	v_pk_mul_f32 v[112:113], v[112:113], v[138:139] op_sel_hi:[1,0]
	v_pk_mul_f32 v[114:115], v[114:115], v[138:139] op_sel_hi:[1,0]
	v_pk_mul_f32 v[108:109], v[108:109], v[138:139] op_sel_hi:[1,0]
	v_pk_mul_f32 v[110:111], v[110:111], v[138:139] op_sel_hi:[1,0]
	v_pk_mul_f32 v[80:81], v[80:81], v[138:139] op_sel_hi:[1,0]
	v_pk_mul_f32 v[82:83], v[82:83], v[138:139] op_sel_hi:[1,0]
	v_pk_mul_f32 v[76:77], v[76:77], v[138:139] op_sel_hi:[1,0]
	v_pk_mul_f32 v[78:79], v[78:79], v[138:139] op_sel_hi:[1,0]
	v_mul_f32_e32 v2, v112, v112
	v_mul_f32_e32 v150, v113, v113
	v_fmac_f32_e32 v2, v114, v114
	v_fmac_f32_e32 v150, v115, v115
	v_fmac_f32_e32 v2, v108, v108
	v_fmac_f32_e32 v150, v109, v109
	v_fmac_f32_e32 v2, v110, v110
	v_fmac_f32_e32 v150, v111, v111
	v_fmac_f32_e32 v2, v80, v80
	v_fmac_f32_e32 v150, v81, v81
	v_fmac_f32_e32 v2, v82, v82
	v_fmac_f32_e32 v150, v83, v83
	v_fmac_f32_e32 v2, v76, v76
	v_fmac_f32_e32 v150, v77, v77
	v_fmac_f32_e32 v2, v78, v78
	v_fmac_f32_e32 v150, v79, v79
	v_add_f32_e32 v2, v2, v150
	v_mov_b32_e32 v150, v2
	s_nop 1
	v_permlane16_swap_b32_e32 v2, v150
	v_add_f32_e32 v2, v2, v150
	v_mov_b32_e32 v150, v2
	s_nop 1
	v_permlane32_swap_b32_e32 v2, v150
	v_add_f32_e32 v2, v2, v150
	v_fmamk_f32 v2, v2, 0x3c800000, v211
	v_rsq_f32_e32 v2, v2
	s_nop 0
	v_mul_f32_e32 v2, s78, v2
	v_pk_mul_f32 v[112:113], v[112:113], v[2:3] op_sel_hi:[1,0]
	v_pk_mul_f32 v[114:115], v[114:115], v[2:3] op_sel_hi:[1,0]
	v_pk_mul_f32 v[108:109], v[108:109], v[2:3] op_sel_hi:[1,0]
	v_pk_mul_f32 v[110:111], v[110:111], v[2:3] op_sel_hi:[1,0]
	v_pk_mul_f32 v[80:81], v[80:81], v[2:3] op_sel_hi:[1,0]
	v_pk_mul_f32 v[82:83], v[82:83], v[2:3] op_sel_hi:[1,0]
	v_pk_mul_f32 v[76:77], v[76:77], v[2:3] op_sel_hi:[1,0]
	v_pk_mul_f32 v[78:79], v[78:79], v[2:3] op_sel_hi:[1,0]
	v_pk_mul_f32 v[112:113], v[112:113], v[176:177]
	v_pk_mul_f32 v[114:115], v[114:115], v[178:179]
	v_pk_mul_f32 v[108:109], v[108:109], v[206:207]
	v_pk_mul_f32 v[110:111], v[110:111], v[208:209]
	v_pk_mul_f32 v[80:81], v[80:81], v[224:225]
	v_pk_mul_f32 v[82:83], v[82:83], v[226:227]
	v_pk_mul_f32 v[76:77], v[76:77], v[228:229]
	v_pk_mul_f32 v[78:79], v[78:79], v[230:231]
	v_cvt_pk_f16_f32 v152, v112, v113
	v_cvt_pk_f16_f32 v153, v114, v115
	v_cvt_pk_f16_f32 v154, v108, v109
	v_cvt_pk_f16_f32 v155, v110, v111
	global_store_dwordx4 v133, v[152:155], s[6:7] nt
	v_cvt_pk_f16_f32 v156, v80, v81
	v_cvt_pk_f16_f32 v157, v82, v83
	v_cvt_pk_f16_f32 v158, v76, v77
	v_cvt_pk_f16_f32 v159, v78, v79
	global_store_dwordx4 v133, v[156:159], s[6:7] offset:2048 nt
	s_add_u32 s6, s4, 0x8100
	s_addc_u32 s7, s5, 0
	v_pk_mul_f32 v[104:105], v[104:105], v[140:141] op_sel_hi:[1,0]
	v_pk_mul_f32 v[106:107], v[106:107], v[140:141] op_sel_hi:[1,0]
	v_pk_mul_f32 v[100:101], v[100:101], v[140:141] op_sel_hi:[1,0]
	v_pk_mul_f32 v[102:103], v[102:103], v[140:141] op_sel_hi:[1,0]
	v_pk_mul_f32 v[72:73], v[72:73], v[140:141] op_sel_hi:[1,0]
	v_pk_mul_f32 v[74:75], v[74:75], v[140:141] op_sel_hi:[1,0]
	v_pk_mul_f32 v[68:69], v[68:69], v[140:141] op_sel_hi:[1,0]
	v_pk_mul_f32 v[70:71], v[70:71], v[140:141] op_sel_hi:[1,0]
	v_mul_f32_e32 v2, v104, v104
	v_mul_f32_e32 v150, v105, v105
	v_fmac_f32_e32 v2, v106, v106
	v_fmac_f32_e32 v150, v107, v107
	v_fmac_f32_e32 v2, v100, v100
	v_fmac_f32_e32 v150, v101, v101
	v_fmac_f32_e32 v2, v102, v102
	v_fmac_f32_e32 v150, v103, v103
	v_fmac_f32_e32 v2, v72, v72
	v_fmac_f32_e32 v150, v73, v73
; #define GAS __attribute__((address_space(1)))
; __host__ __device__ __forceinline__ size_t bl512(size_t row, int col) { return ((row >> 5) * 64 + (size_t)(col >> 3)) * 256 + (row & 31) * 8 + (col & 7); }
; __device__ __forceinline__ float silu_f(float v) { return v * __builtin_amdgcn_rcpf(1.0f + __builtin_amdgcn_exp2f(-v * LOG2E)); }
;     __device__ __forceinline__ void operator()(const f32x4 (&acc)[2][2][4][2], const Unit& u, int wr, int wc, int fr, int fq) const {
;     ...
;                 if (sec == 4 || sec == 5) {
;                     float ss = 0.f;
; #pragma unroll
;                     for (int bj = 0; bj < 2; ++bj)
; #pragma unroll
;                         for (int n = 0; n < 2; ++n) { const f32x4 x = v[bj][n]; ss += (x[0] * x[0] + x[1] * x[1]) + (x[2] * x[2] + x[3] * x[3]); }
;                     ss = row4_sum(ss);
;                     float rn = __builtin_amdgcn_rsqf(ss * (1.0f / 64.0f) + RMS_EPS);
;                     if (sec == 4) rn *= QS;
; #pragma unroll
;                     for (int bj = 0; bj < 2; ++bj)
; #pragma unroll
;                         for (int n = 0; n < 2; ++n) v[bj][n] = v[bj][n] * rn * gain[bj][n];
;                 } else if (sec == 0) {
; #pragma unroll
;                     for (int bj = 0; bj < 2; ++bj)
; #pragma unroll
;                         for (int n = 0; n < 2; ++n) v[bj][n] = v[bj][n] * QS;
;                 } else if (sec == 3 || sec == 7) {
; #pragma unroll
;                     for (int bj = 0; bj < 2; ++bj)
; #pragma unroll
;                         for (int n = 0; n < 2; ++n)
; #pragma unroll
;                             for (int e = 0; e < 4; ++e) v[bj][n][e] = silu_f(v[bj][n][e]);
;                 }
;                 GAS f16* rowp = isqg ? QG + (size_t)dsec * QG_SEC + bl512((size_t)row, cs) : KV + (size_t)row * KVW + dsec * 512 + cs;
; #pragma unroll
;                 for (int bj = 0; bj < 2; ++bj) {
;                     u32x4 w; w.x = pkh(v[bj][0][0], v[bj][0][1]); w.y = pkh(v[bj][0][2], v[bj][0][3]); w.z = pkh(v[bj][1][0], v[bj][1][1]); w.w = pkh(v[bj][1][2], v[bj][1][3]);
;                     *(GAS u32x4*)(rowp + bjstep * bj) = w;
;                 }
	v_fmac_f32_e32 v2, v74, v74
	v_fmac_f32_e32 v150, v75, v75
	v_fmac_f32_e32 v2, v68, v68
	v_fmac_f32_e32 v150, v69, v69
	v_fmac_f32_e32 v2, v70, v70
	v_fmac_f32_e32 v150, v71, v71
	v_add_f32_e32 v2, v2, v150
	v_mov_b32_e32 v150, v2
	s_nop 1
	v_permlane16_swap_b32_e32 v2, v150
	v_add_f32_e32 v2, v2, v150
	v_mov_b32_e32 v150, v2
	s_nop 1
	v_permlane32_swap_b32_e32 v2, v150
	v_add_f32_e32 v2, v2, v150
	v_fmamk_f32 v2, v2, 0x3c800000, v211
	v_rsq_f32_e32 v2, v2
	s_nop 0
	v_mul_f32_e32 v2, s78, v2
	v_pk_mul_f32 v[104:105], v[104:105], v[2:3] op_sel_hi:[1,0]
	v_pk_mul_f32 v[106:107], v[106:107], v[2:3] op_sel_hi:[1,0]
	v_pk_mul_f32 v[100:101], v[100:101], v[2:3] op_sel_hi:[1,0]
	v_pk_mul_f32 v[102:103], v[102:103], v[2:3] op_sel_hi:[1,0]
	v_pk_mul_f32 v[72:73], v[72:73], v[2:3] op_sel_hi:[1,0]
	v_pk_mul_f32 v[74:75], v[74:75], v[2:3] op_sel_hi:[1,0]
	v_pk_mul_f32 v[68:69], v[68:69], v[2:3] op_sel_hi:[1,0]
	v_pk_mul_f32 v[70:71], v[70:71], v[2:3] op_sel_hi:[1,0]
	v_pk_mul_f32 v[104:105], v[104:105], v[176:177]
	v_pk_mul_f32 v[106:107], v[106:107], v[178:179]
	v_pk_mul_f32 v[100:101], v[100:101], v[206:207]
	v_pk_mul_f32 v[102:103], v[102:103], v[208:209]
	v_pk_mul_f32 v[72:73], v[72:73], v[224:225]
	v_pk_mul_f32 v[74:75], v[74:75], v[226:227]
	v_pk_mul_f32 v[68:69], v[68:69], v[228:229]
	v_pk_mul_f32 v[70:71], v[70:71], v[230:231]
	v_cvt_pk_f16_f32 v160, v104, v105
	v_cvt_pk_f16_f32 v161, v106, v107
	v_cvt_pk_f16_f32 v162, v100, v101
	v_cvt_pk_f16_f32 v163, v102, v103
	global_store_dwordx4 v133, v[160:163], s[6:7] nt
	v_cvt_pk_f16_f32 v164, v72, v73
	v_cvt_pk_f16_f32 v165, v74, v75
	v_cvt_pk_f16_f32 v166, v68, v69
	v_cvt_pk_f16_f32 v167, v70, v71
	global_store_dwordx4 v133, v[164:167], s[6:7] offset:2048 nt
	s_add_u32 s6, s4, 0x20000
	s_addc_u32 s7, s5, 0
	v_pk_mul_f32 v[64:65], v[64:65], v[142:143] op_sel_hi:[1,0]
	v_pk_mul_f32 v[66:67], v[66:67], v[142:143] op_sel_hi:[1,0]
	v_pk_mul_f32 v[60:61], v[60:61], v[142:143] op_sel_hi:[1,0]
	v_pk_mul_f32 v[62:63], v[62:63], v[142:143] op_sel_hi:[1,0]
	v_pk_mul_f32 v[32:33], v[32:33], v[142:143] op_sel_hi:[1,0]
	v_pk_mul_f32 v[34:35], v[34:35], v[142:143] op_sel_hi:[1,0]
	v_pk_mul_f32 v[28:29], v[28:29], v[142:143] op_sel_hi:[1,0]
	v_pk_mul_f32 v[30:31], v[30:31], v[142:143] op_sel_hi:[1,0]
	v_mul_f32_e32 v2, v64, v64
	v_mul_f32_e32 v150, v65, v65
	v_fmac_f32_e32 v2, v66, v66
	v_fmac_f32_e32 v150, v67, v67
	v_fmac_f32_e32 v2, v60, v60
	v_fmac_f32_e32 v150, v61, v61
	v_fmac_f32_e32 v2, v62, v62
	v_fmac_f32_e32 v150, v63, v63
	v_fmac_f32_e32 v2, v32, v32
	v_fmac_f32_e32 v150, v33, v33
	v_fmac_f32_e32 v2, v34, v34
	v_fmac_f32_e32 v150, v35, v35
	v_fmac_f32_e32 v2, v28, v28
	v_fmac_f32_e32 v150, v29, v29
	v_fmac_f32_e32 v2, v30, v30
	v_fmac_f32_e32 v150, v31, v31
	v_add_f32_e32 v2, v2, v150
	v_mov_b32_e32 v150, v2
	s_nop 1
	v_permlane16_swap_b32_e32 v2, v150
	v_add_f32_e32 v2, v2, v150
	v_mov_b32_e32 v150, v2
	s_nop 1
	v_permlane32_swap_b32_e32 v2, v150
	v_add_f32_e32 v2, v2, v150
	v_fmamk_f32 v2, v2, 0x3c800000, v211
	v_rsq_f32_e32 v2, v2
	s_nop 0
	v_mul_f32_e32 v2, s78, v2
	v_pk_mul_f32 v[64:65], v[64:65], v[2:3] op_sel_hi:[1,0]
	v_pk_mul_f32 v[66:67], v[66:67], v[2:3] op_sel_hi:[1,0]
	v_pk_mul_f32 v[60:61], v[60:61], v[2:3] op_sel_hi:[1,0]
	v_pk_mul_f32 v[62:63], v[62:63], v[2:3] op_sel_hi:[1,0]
	v_pk_mul_f32 v[32:33], v[32:33], v[2:3] op_sel_hi:[1,0]
	v_pk_mul_f32 v[34:35], v[34:35], v[2:3] op_sel_hi:[1,0]
	v_pk_mul_f32 v[28:29], v[28:29], v[2:3] op_sel_hi:[1,0]
	v_pk_mul_f32 v[30:31], v[30:31], v[2:3] op_sel_hi:[1,0]
	v_pk_mul_f32 v[64:65], v[64:65], v[176:177]
	v_pk_mul_f32 v[66:67], v[66:67], v[178:179]
	v_pk_mul_f32 v[60:61], v[60:61], v[206:207]
	v_pk_mul_f32 v[62:63], v[62:63], v[208:209]
	v_pk_mul_f32 v[32:33], v[32:33], v[224:225]
	v_pk_mul_f32 v[34:35], v[34:35], v[226:227]
	v_pk_mul_f32 v[28:29], v[28:29], v[228:229]
	v_pk_mul_f32 v[30:31], v[30:31], v[230:231]
	v_cvt_pk_f16_f32 v152, v64, v65
	v_cvt_pk_f16_f32 v153, v66, v67
	v_cvt_pk_f16_f32 v154, v60, v61
	v_cvt_pk_f16_f32 v155, v62, v63
	global_store_dwordx4 v133, v[152:155], s[6:7] nt
	v_cvt_pk_f16_f32 v156, v32, v33
	v_cvt_pk_f16_f32 v157, v34, v35
	v_cvt_pk_f16_f32 v158, v28, v29
	v_cvt_pk_f16_f32 v159, v30, v31
	global_store_dwordx4 v133, v[156:159], s[6:7] offset:2048 nt
	s_add_u32 s6, s4, 0x20100
	s_addc_u32 s7, s5, 0
	v_pk_mul_f32 v[56:57], v[56:57], v[144:145] op_sel_hi:[1,0]
	v_pk_mul_f32 v[58:59], v[58:59], v[144:145] op_sel_hi:[1,0]
	v_pk_mul_f32 v[52:53], v[52:53], v[144:145] op_sel_hi:[1,0]
	v_pk_mul_f32 v[54:55], v[54:55], v[144:145] op_sel_hi:[1,0]
	v_pk_mul_f32 v[24:25], v[24:25], v[144:145] op_sel_hi:[1,0]
	v_pk_mul_f32 v[26:27], v[26:27], v[144:145] op_sel_hi:[1,0]
	v_pk_mul_f32 v[20:21], v[20:21], v[144:145] op_sel_hi:[1,0]
	v_pk_mul_f32 v[22:23], v[22:23], v[144:145] op_sel_hi:[1,0]
	v_mul_f32_e32 v2, v56, v56
	v_mul_f32_e32 v150, v57, v57
	v_fmac_f32_e32 v2, v58, v58
	v_fmac_f32_e32 v150, v59, v59
	v_fmac_f32_e32 v2, v52, v52
	v_fmac_f32_e32 v150, v53, v53
	v_fmac_f32_e32 v2, v54, v54
	v_fmac_f32_e32 v150, v55, v55
	v_fmac_f32_e32 v2, v24, v24
	v_fmac_f32_e32 v150, v25, v25
	v_fmac_f32_e32 v2, v26, v26
	v_fmac_f32_e32 v150, v27, v27
	v_fmac_f32_e32 v2, v20, v20
	v_fmac_f32_e32 v150, v21, v21
	v_fmac_f32_e32 v2, v22, v22
	v_fmac_f32_e32 v150, v23, v23
	v_add_f32_e32 v2, v2, v150
	v_mov_b32_e32 v150, v2
	s_nop 1
	v_permlane16_swap_b32_e32 v2, v150
	v_add_f32_e32 v2, v2, v150
	v_mov_b32_e32 v150, v2
	s_nop 1
	v_permlane32_swap_b32_e32 v2, v150
	v_add_f32_e32 v2, v2, v150
	v_fmamk_f32 v2, v2, 0x3c800000, v211
	v_rsq_f32_e32 v2, v2
	s_nop 0
	v_mul_f32_e32 v2, s78, v2
	v_pk_mul_f32 v[56:57], v[56:57], v[2:3] op_sel_hi:[1,0]
; #define GAS __attribute__((address_space(1)))
; __host__ __device__ __forceinline__ size_t bl512(size_t row, int col) { return ((row >> 5) * 64 + (size_t)(col >> 3)) * 256 + (row & 31) * 8 + (col & 7); }
; __device__ __forceinline__ float silu_f(float v) { return v * __builtin_amdgcn_rcpf(1.0f + __builtin_amdgcn_exp2f(-v * LOG2E)); }
;     __device__ __forceinline__ void operator()(const f32x4 (&acc)[2][2][4][2], const Unit& u, int wr, int wc, int fr, int fq) const {
;     ...
;                 if (sec == 4 || sec == 5) {
;                     float ss = 0.f;
; #pragma unroll
;                     for (int bj = 0; bj < 2; ++bj)
; #pragma unroll
;                         for (int n = 0; n < 2; ++n) { const f32x4 x = v[bj][n]; ss += (x[0] * x[0] + x[1] * x[1]) + (x[2] * x[2] + x[3] * x[3]); }
;                     ss = row4_sum(ss);
;                     float rn = __builtin_amdgcn_rsqf(ss * (1.0f / 64.0f) + RMS_EPS);
;                     if (sec == 4) rn *= QS;
; #pragma unroll
;                     for (int bj = 0; bj < 2; ++bj)
; #pragma unroll
;                         for (int n = 0; n < 2; ++n) v[bj][n] = v[bj][n] * rn * gain[bj][n];
;                 } else if (sec == 0) {
; #pragma unroll
;                     for (int bj = 0; bj < 2; ++bj)
; #pragma unroll
;                         for (int n = 0; n < 2; ++n) v[bj][n] = v[bj][n] * QS;
;                 } else if (sec == 3 || sec == 7) {
; #pragma unroll
;                     for (int bj = 0; bj < 2; ++bj)
; #pragma unroll
;                         for (int n = 0; n < 2; ++n)
; #pragma unroll
;                             for (int e = 0; e < 4; ++e) v[bj][n][e] = silu_f(v[bj][n][e]);
;                 }
;                 GAS f16* rowp = isqg ? QG + (size_t)dsec * QG_SEC + bl512((size_t)row, cs) : KV + (size_t)row * KVW + dsec * 512 + cs;
; #pragma unroll
;                 for (int bj = 0; bj < 2; ++bj) {
;                     u32x4 w; w.x = pkh(v[bj][0][0], v[bj][0][1]); w.y = pkh(v[bj][0][2], v[bj][0][3]); w.z = pkh(v[bj][1][0], v[bj][1][1]); w.w = pkh(v[bj][1][2], v[bj][1][3]);
;                     *(GAS u32x4*)(rowp + bjstep * bj) = w;
;                 }
	v_pk_mul_f32 v[58:59], v[58:59], v[2:3] op_sel_hi:[1,0]
	v_pk_mul_f32 v[52:53], v[52:53], v[2:3] op_sel_hi:[1,0]
	v_pk_mul_f32 v[54:55], v[54:55], v[2:3] op_sel_hi:[1,0]
	v_pk_mul_f32 v[24:25], v[24:25], v[2:3] op_sel_hi:[1,0]
	v_pk_mul_f32 v[26:27], v[26:27], v[2:3] op_sel_hi:[1,0]
	v_pk_mul_f32 v[20:21], v[20:21], v[2:3] op_sel_hi:[1,0]
	v_pk_mul_f32 v[22:23], v[22:23], v[2:3] op_sel_hi:[1,0]
	v_pk_mul_f32 v[56:57], v[56:57], v[176:177]
	v_pk_mul_f32 v[58:59], v[58:59], v[178:179]
	v_pk_mul_f32 v[52:53], v[52:53], v[206:207]
	v_pk_mul_f32 v[54:55], v[54:55], v[208:209]
	v_pk_mul_f32 v[24:25], v[24:25], v[224:225]
	v_pk_mul_f32 v[26:27], v[26:27], v[226:227]
	v_pk_mul_f32 v[20:21], v[20:21], v[228:229]
	v_pk_mul_f32 v[22:23], v[22:23], v[230:231]
	v_cvt_pk_f16_f32 v160, v56, v57
	v_cvt_pk_f16_f32 v161, v58, v59
	v_cvt_pk_f16_f32 v162, v52, v53
	v_cvt_pk_f16_f32 v163, v54, v55
	global_store_dwordx4 v133, v[160:163], s[6:7] nt
	v_cvt_pk_f16_f32 v164, v24, v25
	v_cvt_pk_f16_f32 v165, v26, v27
	v_cvt_pk_f16_f32 v166, v20, v21
	v_cvt_pk_f16_f32 v167, v22, v23
	global_store_dwordx4 v133, v[164:167], s[6:7] offset:2048 nt
	s_add_u32 s6, s4, 0x28000
	s_addc_u32 s7, s5, 0
	v_pk_mul_f32 v[48:49], v[48:49], v[146:147] op_sel_hi:[1,0]
	v_pk_mul_f32 v[50:51], v[50:51], v[146:147] op_sel_hi:[1,0]
	v_pk_mul_f32 v[44:45], v[44:45], v[146:147] op_sel_hi:[1,0]
	v_pk_mul_f32 v[46:47], v[46:47], v[146:147] op_sel_hi:[1,0]
	v_pk_mul_f32 v[16:17], v[16:17], v[146:147] op_sel_hi:[1,0]
	v_pk_mul_f32 v[18:19], v[18:19], v[146:147] op_sel_hi:[1,0]
	v_pk_mul_f32 v[12:13], v[12:13], v[146:147] op_sel_hi:[1,0]
	v_pk_mul_f32 v[14:15], v[14:15], v[146:147] op_sel_hi:[1,0]
	v_mul_f32_e32 v2, v48, v48
	v_mul_f32_e32 v150, v49, v49
	v_fmac_f32_e32 v2, v50, v50
	v_fmac_f32_e32 v150, v51, v51
	v_fmac_f32_e32 v2, v44, v44
	v_fmac_f32_e32 v150, v45, v45
	v_fmac_f32_e32 v2, v46, v46
	v_fmac_f32_e32 v150, v47, v47
	v_fmac_f32_e32 v2, v16, v16
	v_fmac_f32_e32 v150, v17, v17
	v_fmac_f32_e32 v2, v18, v18
	v_fmac_f32_e32 v150, v19, v19
	v_fmac_f32_e32 v2, v12, v12
	v_fmac_f32_e32 v150, v13, v13
	v_fmac_f32_e32 v2, v14, v14
	v_fmac_f32_e32 v150, v15, v15
	v_add_f32_e32 v2, v2, v150
	v_mov_b32_e32 v150, v2
	s_nop 1
	v_permlane16_swap_b32_e32 v2, v150
	v_add_f32_e32 v2, v2, v150
	v_mov_b32_e32 v150, v2
	s_nop 1
	v_permlane32_swap_b32_e32 v2, v150
	v_add_f32_e32 v2, v2, v150
	v_fmamk_f32 v2, v2, 0x3c800000, v211
	v_rsq_f32_e32 v2, v2
	s_nop 0
	v_mul_f32_e32 v2, s78, v2
	v_pk_mul_f32 v[48:49], v[48:49], v[2:3] op_sel_hi:[1,0]
	v_pk_mul_f32 v[50:51], v[50:51], v[2:3] op_sel_hi:[1,0]
	v_pk_mul_f32 v[44:45], v[44:45], v[2:3] op_sel_hi:[1,0]
	v_pk_mul_f32 v[46:47], v[46:47], v[2:3] op_sel_hi:[1,0]
	v_pk_mul_f32 v[16:17], v[16:17], v[2:3] op_sel_hi:[1,0]
	v_pk_mul_f32 v[18:19], v[18:19], v[2:3] op_sel_hi:[1,0]
	v_pk_mul_f32 v[12:13], v[12:13], v[2:3] op_sel_hi:[1,0]
	v_pk_mul_f32 v[14:15], v[14:15], v[2:3] op_sel_hi:[1,0]
	v_pk_mul_f32 v[48:49], v[48:49], v[176:177]
	v_pk_mul_f32 v[50:51], v[50:51], v[178:179]
	v_pk_mul_f32 v[44:45], v[44:45], v[206:207]
	v_pk_mul_f32 v[46:47], v[46:47], v[208:209]
	v_pk_mul_f32 v[16:17], v[16:17], v[224:225]
	v_pk_mul_f32 v[18:19], v[18:19], v[226:227]
	v_pk_mul_f32 v[12:13], v[12:13], v[228:229]
	v_pk_mul_f32 v[14:15], v[14:15], v[230:231]
	v_cvt_pk_f16_f32 v152, v48, v49
	v_cvt_pk_f16_f32 v153, v50, v51
	v_cvt_pk_f16_f32 v154, v44, v45
	v_cvt_pk_f16_f32 v155, v46, v47
	global_store_dwordx4 v133, v[152:155], s[6:7] nt
	v_cvt_pk_f16_f32 v156, v16, v17
	v_cvt_pk_f16_f32 v157, v18, v19
	v_cvt_pk_f16_f32 v158, v12, v13
	v_cvt_pk_f16_f32 v159, v14, v15
	global_store_dwordx4 v133, v[156:159], s[6:7] offset:2048 nt
	s_add_u32 s6, s4, 0x28100
	s_addc_u32 s7, s5, 0
	v_pk_mul_f32 v[40:41], v[40:41], v[148:149] op_sel_hi:[1,0]
	v_pk_mul_f32 v[42:43], v[42:43], v[148:149] op_sel_hi:[1,0]
	v_pk_mul_f32 v[36:37], v[36:37], v[148:149] op_sel_hi:[1,0]
	v_pk_mul_f32 v[38:39], v[38:39], v[148:149] op_sel_hi:[1,0]
	v_pk_mul_f32 v[8:9], v[8:9], v[148:149] op_sel_hi:[1,0]
	v_pk_mul_f32 v[10:11], v[10:11], v[148:149] op_sel_hi:[1,0]
	v_pk_mul_f32 v[4:5], v[4:5], v[148:149] op_sel_hi:[1,0]
	v_pk_mul_f32 v[6:7], v[6:7], v[148:149] op_sel_hi:[1,0]
	v_mul_f32_e32 v2, v40, v40
	v_mul_f32_e32 v150, v41, v41
	v_fmac_f32_e32 v2, v42, v42
	v_fmac_f32_e32 v150, v43, v43
	v_fmac_f32_e32 v2, v36, v36
	v_fmac_f32_e32 v150, v37, v37
	v_fmac_f32_e32 v2, v38, v38
	v_fmac_f32_e32 v150, v39, v39
	v_fmac_f32_e32 v2, v8, v8
	v_fmac_f32_e32 v150, v9, v9
	v_fmac_f32_e32 v2, v10, v10
	v_fmac_f32_e32 v150, v11, v11
	v_fmac_f32_e32 v2, v4, v4
	v_fmac_f32_e32 v150, v5, v5
	v_fmac_f32_e32 v2, v6, v6
	v_fmac_f32_e32 v150, v7, v7
	v_add_f32_e32 v2, v2, v150
	v_mov_b32_e32 v150, v2
	s_nop 1
	v_permlane16_swap_b32_e32 v2, v150
	v_add_f32_e32 v2, v2, v150
	v_mov_b32_e32 v150, v2
	s_nop 1
	v_permlane32_swap_b32_e32 v2, v150
	v_add_f32_e32 v2, v2, v150
	v_fmamk_f32 v2, v2, 0x3c800000, v211
	v_rsq_f32_e32 v2, v2
	s_nop 0
	v_mul_f32_e32 v2, s78, v2
	v_pk_mul_f32 v[40:41], v[40:41], v[2:3] op_sel_hi:[1,0]
	v_pk_mul_f32 v[42:43], v[42:43], v[2:3] op_sel_hi:[1,0]
	v_pk_mul_f32 v[36:37], v[36:37], v[2:3] op_sel_hi:[1,0]
	v_pk_mul_f32 v[38:39], v[38:39], v[2:3] op_sel_hi:[1,0]
	v_pk_mul_f32 v[8:9], v[8:9], v[2:3] op_sel_hi:[1,0]
	v_pk_mul_f32 v[10:11], v[10:11], v[2:3] op_sel_hi:[1,0]
	v_pk_mul_f32 v[4:5], v[4:5], v[2:3] op_sel_hi:[1,0]
	v_pk_mul_f32 v[6:7], v[6:7], v[2:3] op_sel_hi:[1,0]
	v_pk_mul_f32 v[40:41], v[40:41], v[176:177]
	v_pk_mul_f32 v[42:43], v[42:43], v[178:179]
	v_pk_mul_f32 v[36:37], v[36:37], v[206:207]
	v_pk_mul_f32 v[38:39], v[38:39], v[208:209]
	v_pk_mul_f32 v[8:9], v[8:9], v[224:225]
	v_pk_mul_f32 v[10:11], v[10:11], v[226:227]
	v_pk_mul_f32 v[4:5], v[4:5], v[228:229]
	v_pk_mul_f32 v[6:7], v[6:7], v[230:231]
	v_cvt_pk_f16_f32 v160, v40, v41
	v_cvt_pk_f16_f32 v161, v42, v43
	v_cvt_pk_f16_f32 v162, v36, v37
	v_cvt_pk_f16_f32 v163, v38, v39
	global_store_dwordx4 v133, v[160:163], s[6:7] nt
	v_cvt_pk_f16_f32 v164, v8, v9
	v_cvt_pk_f16_f32 v165, v10, v11
	v_cvt_pk_f16_f32 v166, v4, v5
	v_cvt_pk_f16_f32 v167, v6, v7
	global_store_dwordx4 v133, v[164:167], s[6:7] offset:2048 nt
	s_branch .Lepi_done_g1
; #define LAS __attribute__((address_space(3)))
; #define GAS __attribute__((address_space(1)))
;     __device__ __forceinline__ void operator()(const f32x4 (&acc)[2][2][4][2], const Unit& u, int wr, int wc, int fr, int fq) const {
;     ...
;         if (sec == 4 || sec == 5) {
;             const GAS float* g = (sec == 4) ? gq : gk;
; #pragma unroll
;             for (int bj = 0; bj < 2; ++bj)
; #pragma unroll
;                 for (int n = 0; n < 2; ++n) gain[bj][n] = *(const GAS f32x4*)(g + 32 * bj + 8 * fq + 4 * n);
;         }
;         const LAS int* tags = (const LAS int*)(rsc + 2048);
;         const int slot = (tags[0] == u.pm) ? 0 : (tags[1] == u.pm) ? 1 : -1;
;         const LAS float* rtab = (const LAS float*)rsc + (slot > 0 ? 256 : 0) + wr * 64 + fr;
; #pragma unroll
;         for (int ai = 0; ai < 2; ++ai)
; #pragma unroll
;             for (int m = 0; m < 4; ++m) {
;                 const int row = row0 + ai * HALF + m * 16;
;                 float rs;
;                 if (slot >= 0) rs = rtab[ai * HALF + m * 16];
;                 else {
;                     const f32x4 pv = *(const GAS f32x4*)(part + (size_t)row * 16 + fq * 4);
;                     float s = (pv[0] + pv[1]) + (pv[2] + pv[3]);
;                     s = row4_sum(s);
;                     rs = __builtin_amdgcn_rsqf(s * (1.0f / DM) + RMS_EPS);
;                 }
;                 f32x4 v[2][2];
; #pragma unroll
;                 for (int bj = 0; bj < 2; ++bj)
; #pragma unroll
;                     for (int n = 0; n < 2; ++n) v[bj][n] = acc[ai][bj][m][n] * rs;
;                 if (sec == 4 || sec == 5) {
;                     float ss = 0.f;
; #pragma unroll
;                     for (int bj = 0; bj < 2; ++bj)
; #pragma unroll
;                         for (int n = 0; n < 2; ++n) { const f32x4 x = v[bj][n]; ss += (x[0] * x[0] + x[1] * x[1]) + (x[2] * x[2] + x[3] * x[3]); }
;                     ss = row4_sum(ss);
;                     float rn = __builtin_amdgcn_rsqf(ss * (1.0f / 64.0f) + RMS_EPS);
;                     if (sec == 4) rn *= QS;
; #pragma unroll
;                     for (int bj = 0; bj < 2; ++bj)
; #pragma unroll
;                         for (int n = 0; n < 2; ++n) v[bj][n] = v[bj][n] * rn * gain[bj][n];
.Lepi_kn:
	s_and_b32 s0, s70, 1
	s_lshl_b32 s0, s0, 10
	v_add_u32_e32 v132, s0, v219
	ds_read_b32 v134, v132
	ds_read_b32 v136, v132 offset:64
	ds_read_b32 v138, v132 offset:128
	ds_read_b32 v140, v132 offset:192
	ds_read_b32 v142, v132 offset:512
	ds_read_b32 v144, v132 offset:576
	ds_read_b32 v146, v132 offset:640
	ds_read_b32 v148, v132 offset:704
	s_lshr_b32 s0, s69, 2
	s_and_b32 s1, s69, 1
	v_lshl_add_u32 v133, s68, 8, v187
	v_lshlrev_b32_e32 v133, 12, v133
	v_lshl_add_u32 v133, v220, 1, v133
	s_lshl_b32 s0, s0, 10
	s_lshl_b32 s1, s1, 9
	s_add_u32 s0, s0, s1
	s_add_u32 s4, s8, s0
	s_addc_u32 s5, s9, 0
	v_readlane_b32 s10, v252, 19
	v_readlane_b32 s11, v252, 20
	s_lshl_b32 s0, s22, 2
	s_nop 0
	s_add_u32 s10, s10, s0
	s_addc_u32 s11, s11, 0
	s_nop 3
	global_load_dwordx4 v[176:179], v222, s[10:11]
	global_load_dwordx4 v[206:209], v222, s[10:11] offset:16
	global_load_dwordx4 v[224:227], v222, s[10:11] offset:128
	global_load_dwordx4 v[228:231], v222, s[10:11] offset:144
	s_waitcnt vmcnt(0)
	s_waitcnt lgkmcnt(0)
	s_mov_b32 s6, s4
	s_mov_b32 s7, s5
	v_pk_mul_f32 v[128:129], v[128:129], v[134:135] op_sel_hi:[1,0]
	v_pk_mul_f32 v[130:131], v[130:131], v[134:135] op_sel_hi:[1,0]
	v_pk_mul_f32 v[124:125], v[124:125], v[134:135] op_sel_hi:[1,0]
	v_pk_mul_f32 v[126:127], v[126:127], v[134:135] op_sel_hi:[1,0]
	v_pk_mul_f32 v[96:97], v[96:97], v[134:135] op_sel_hi:[1,0]
	v_pk_mul_f32 v[98:99], v[98:99], v[134:135] op_sel_hi:[1,0]
	v_pk_mul_f32 v[92:93], v[92:93], v[134:135] op_sel_hi:[1,0]
	v_pk_mul_f32 v[94:95], v[94:95], v[134:135] op_sel_hi:[1,0]
	v_mul_f32_e32 v2, v128, v128
	v_mul_f32_e32 v150, v129, v129
	v_fmac_f32_e32 v2, v130, v130
	v_fmac_f32_e32 v150, v131, v131
	v_fmac_f32_e32 v2, v124, v124
	v_fmac_f32_e32 v150, v125, v125
	v_fmac_f32_e32 v2, v126, v126
	v_fmac_f32_e32 v150, v127, v127
	v_fmac_f32_e32 v2, v96, v96
	v_fmac_f32_e32 v150, v97, v97
	v_fmac_f32_e32 v2, v98, v98
	v_fmac_f32_e32 v150, v99, v99
	v_fmac_f32_e32 v2, v92, v92
	v_fmac_f32_e32 v150, v93, v93
	v_fmac_f32_e32 v2, v94, v94
	v_fmac_f32_e32 v150, v95, v95
	v_add_f32_e32 v2, v2, v150
	v_mov_b32_e32 v150, v2
	s_nop 1
	v_permlane16_swap_b32_e32 v2, v150
	v_add_f32_e32 v2, v2, v150
	v_mov_b32_e32 v150, v2
	s_nop 1
	v_permlane32_swap_b32_e32 v2, v150
	v_add_f32_e32 v2, v2, v150
	v_fmamk_f32 v2, v2, 0x3c800000, v211
	v_rsq_f32_e32 v2, v2
	s_nop 0
	v_pk_mul_f32 v[128:129], v[128:129], v[2:3] op_sel_hi:[1,0]
	v_pk_mul_f32 v[130:131], v[130:131], v[2:3] op_sel_hi:[1,0]
	v_pk_mul_f32 v[124:125], v[124:125], v[2:3] op_sel_hi:[1,0]
	v_pk_mul_f32 v[126:127], v[126:127], v[2:3] op_sel_hi:[1,0]
	v_pk_mul_f32 v[96:97], v[96:97], v[2:3] op_sel_hi:[1,0]
	v_pk_mul_f32 v[98:99], v[98:99], v[2:3] op_sel_hi:[1,0]
	v_pk_mul_f32 v[92:93], v[92:93], v[2:3] op_sel_hi:[1,0]
	v_pk_mul_f32 v[94:95], v[94:95], v[2:3] op_sel_hi:[1,0]
	v_pk_mul_f32 v[128:129], v[128:129], v[176:177]
	v_pk_mul_f32 v[130:131], v[130:131], v[178:179]
	v_pk_mul_f32 v[124:125], v[124:125], v[206:207]
	v_pk_mul_f32 v[126:127], v[126:127], v[208:209]
	v_pk_mul_f32 v[96:97], v[96:97], v[224:225]
	v_pk_mul_f32 v[98:99], v[98:99], v[226:227]
	v_pk_mul_f32 v[92:93], v[92:93], v[228:229]
	v_pk_mul_f32 v[94:95], v[94:95], v[230:231]
	v_cvt_pk_f16_f32 v152, v128, v129
	v_cvt_pk_f16_f32 v153, v130, v131
	v_cvt_pk_f16_f32 v154, v124, v125
	v_cvt_pk_f16_f32 v155, v126, v127
	global_store_dwordx4 v133, v[152:155], s[6:7] nt
	v_cvt_pk_f16_f32 v156, v96, v97
	v_cvt_pk_f16_f32 v157, v98, v99
	v_cvt_pk_f16_f32 v158, v92, v93
	v_cvt_pk_f16_f32 v159, v94, v95
	global_store_dwordx4 v133, v[156:159], s[6:7] offset:64 nt
	s_add_u32 s6, s4, 0x10000
	s_addc_u32 s7, s5, 0
	v_pk_mul_f32 v[120:121], v[120:121], v[136:137] op_sel_hi:[1,0]
	v_pk_mul_f32 v[122:123], v[122:123], v[136:137] op_sel_hi:[1,0]
	v_pk_mul_f32 v[116:117], v[116:117], v[136:137] op_sel_hi:[1,0]
	v_pk_mul_f32 v[118:119], v[118:119], v[136:137] op_sel_hi:[1,0]
	v_pk_mul_f32 v[88:89], v[88:89], v[136:137] op_sel_hi:[1,0]
	v_pk_mul_f32 v[90:91], v[90:91], v[136:137] op_sel_hi:[1,0]
	v_pk_mul_f32 v[84:85], v[84:85], v[136:137] op_sel_hi:[1,0]
	v_pk_mul_f32 v[86:87], v[86:87], v[136:137] op_sel_hi:[1,0]
	v_mul_f32_e32 v2, v120, v120
	v_mul_f32_e32 v150, v121, v121
	v_fmac_f32_e32 v2, v122, v122
	v_fmac_f32_e32 v150, v123, v123
	v_fmac_f32_e32 v2, v116, v116
	v_fmac_f32_e32 v150, v117, v117
	v_fmac_f32_e32 v2, v118, v118
	v_fmac_f32_e32 v150, v119, v119
	v_fmac_f32_e32 v2, v88, v88
	v_fmac_f32_e32 v150, v89, v89
	v_fmac_f32_e32 v2, v90, v90
	v_fmac_f32_e32 v150, v91, v91
	v_fmac_f32_e32 v2, v84, v84
	v_fmac_f32_e32 v150, v85, v85
	v_fmac_f32_e32 v2, v86, v86
	v_fmac_f32_e32 v150, v87, v87
	v_add_f32_e32 v2, v2, v150
	v_mov_b32_e32 v150, v2
	s_nop 1
	v_permlane16_swap_b32_e32 v2, v150
	v_add_f32_e32 v2, v2, v150
	v_mov_b32_e32 v150, v2
	s_nop 1
	v_permlane32_swap_b32_e32 v2, v150
	v_add_f32_e32 v2, v2, v150
	v_fmamk_f32 v2, v2, 0x3c800000, v211
	v_rsq_f32_e32 v2, v2
	s_nop 0
	v_pk_mul_f32 v[120:121], v[120:121], v[2:3] op_sel_hi:[1,0]
	v_pk_mul_f32 v[122:123], v[122:123], v[2:3] op_sel_hi:[1,0]
	v_pk_mul_f32 v[116:117], v[116:117], v[2:3] op_sel_hi:[1,0]
	v_pk_mul_f32 v[118:119], v[118:119], v[2:3] op_sel_hi:[1,0]
	v_pk_mul_f32 v[88:89], v[88:89], v[2:3] op_sel_hi:[1,0]
	v_pk_mul_f32 v[90:91], v[90:91], v[2:3] op_sel_hi:[1,0]
	v_pk_mul_f32 v[84:85], v[84:85], v[2:3] op_sel_hi:[1,0]
	v_pk_mul_f32 v[86:87], v[86:87], v[2:3] op_sel_hi:[1,0]
	v_pk_mul_f32 v[120:121], v[120:121], v[176:177]
	v_pk_mul_f32 v[122:123], v[122:123], v[178:179]
	v_pk_mul_f32 v[116:117], v[116:117], v[206:207]
	v_pk_mul_f32 v[118:119], v[118:119], v[208:209]
	v_pk_mul_f32 v[88:89], v[88:89], v[224:225]
; #define GAS __attribute__((address_space(1)))
; __host__ __device__ __forceinline__ size_t bl512(size_t row, int col) { return ((row >> 5) * 64 + (size_t)(col >> 3)) * 256 + (row & 31) * 8 + (col & 7); }
; __device__ __forceinline__ float silu_f(float v) { return v * __builtin_amdgcn_rcpf(1.0f + __builtin_amdgcn_exp2f(-v * LOG2E)); }
;     __device__ __forceinline__ void operator()(const f32x4 (&acc)[2][2][4][2], const Unit& u, int wr, int wc, int fr, int fq) const {
;     ...
;                 if (sec == 4 || sec == 5) {
;                     float ss = 0.f;
; #pragma unroll
;                     for (int bj = 0; bj < 2; ++bj)
; #pragma unroll
;                         for (int n = 0; n < 2; ++n) { const f32x4 x = v[bj][n]; ss += (x[0] * x[0] + x[1] * x[1]) + (x[2] * x[2] + x[3] * x[3]); }
;                     ss = row4_sum(ss);
;                     float rn = __builtin_amdgcn_rsqf(ss * (1.0f / 64.0f) + RMS_EPS);
;                     if (sec == 4) rn *= QS;
; #pragma unroll
;                     for (int bj = 0; bj < 2; ++bj)
; #pragma unroll
;                         for (int n = 0; n < 2; ++n) v[bj][n] = v[bj][n] * rn * gain[bj][n];
;                 } else if (sec == 0) {
; #pragma unroll
;                     for (int bj = 0; bj < 2; ++bj)
; #pragma unroll
;                         for (int n = 0; n < 2; ++n) v[bj][n] = v[bj][n] * QS;
;                 } else if (sec == 3 || sec == 7) {
; #pragma unroll
;                     for (int bj = 0; bj < 2; ++bj)
; #pragma unroll
;                         for (int n = 0; n < 2; ++n)
; #pragma unroll
;                             for (int e = 0; e < 4; ++e) v[bj][n][e] = silu_f(v[bj][n][e]);
;                 }
;                 GAS f16* rowp = isqg ? QG + (size_t)dsec * QG_SEC + bl512((size_t)row, cs) : KV + (size_t)row * KVW + dsec * 512 + cs;
; #pragma unroll
;                 for (int bj = 0; bj < 2; ++bj) {
;                     u32x4 w; w.x = pkh(v[bj][0][0], v[bj][0][1]); w.y = pkh(v[bj][0][2], v[bj][0][3]); w.z = pkh(v[bj][1][0], v[bj][1][1]); w.w = pkh(v[bj][1][2], v[bj][1][3]);
;                     *(GAS u32x4*)(rowp + bjstep * bj) = w;
;                 }
	v_pk_mul_f32 v[90:91], v[90:91], v[226:227]
	v_pk_mul_f32 v[84:85], v[84:85], v[228:229]
	v_pk_mul_f32 v[86:87], v[86:87], v[230:231]
	v_cvt_pk_f16_f32 v160, v120, v121
	v_cvt_pk_f16_f32 v161, v122, v123
	v_cvt_pk_f16_f32 v162, v116, v117
	v_cvt_pk_f16_f32 v163, v118, v119
	global_store_dwordx4 v133, v[160:163], s[6:7] nt
	v_cvt_pk_f16_f32 v164, v88, v89
	v_cvt_pk_f16_f32 v165, v90, v91
	v_cvt_pk_f16_f32 v166, v84, v85
	v_cvt_pk_f16_f32 v167, v86, v87
	global_store_dwordx4 v133, v[164:167], s[6:7] offset:64 nt
	s_add_u32 s6, s4, 0x20000
	s_addc_u32 s7, s5, 0
	v_pk_mul_f32 v[112:113], v[112:113], v[138:139] op_sel_hi:[1,0]
	v_pk_mul_f32 v[114:115], v[114:115], v[138:139] op_sel_hi:[1,0]
	v_pk_mul_f32 v[108:109], v[108:109], v[138:139] op_sel_hi:[1,0]
	v_pk_mul_f32 v[110:111], v[110:111], v[138:139] op_sel_hi:[1,0]
	v_pk_mul_f32 v[80:81], v[80:81], v[138:139] op_sel_hi:[1,0]
	v_pk_mul_f32 v[82:83], v[82:83], v[138:139] op_sel_hi:[1,0]
	v_pk_mul_f32 v[76:77], v[76:77], v[138:139] op_sel_hi:[1,0]
	v_pk_mul_f32 v[78:79], v[78:79], v[138:139] op_sel_hi:[1,0]
	v_mul_f32_e32 v2, v112, v112
	v_mul_f32_e32 v150, v113, v113
	v_fmac_f32_e32 v2, v114, v114
	v_fmac_f32_e32 v150, v115, v115
	v_fmac_f32_e32 v2, v108, v108
	v_fmac_f32_e32 v150, v109, v109
	v_fmac_f32_e32 v2, v110, v110
	v_fmac_f32_e32 v150, v111, v111
	v_fmac_f32_e32 v2, v80, v80
	v_fmac_f32_e32 v150, v81, v81
	v_fmac_f32_e32 v2, v82, v82
	v_fmac_f32_e32 v150, v83, v83
	v_fmac_f32_e32 v2, v76, v76
	v_fmac_f32_e32 v150, v77, v77
	v_fmac_f32_e32 v2, v78, v78
	v_fmac_f32_e32 v150, v79, v79
	v_add_f32_e32 v2, v2, v150
	v_mov_b32_e32 v150, v2
	s_nop 1
	v_permlane16_swap_b32_e32 v2, v150
	v_add_f32_e32 v2, v2, v150
	v_mov_b32_e32 v150, v2
	s_nop 1
	v_permlane32_swap_b32_e32 v2, v150
	v_add_f32_e32 v2, v2, v150
	v_fmamk_f32 v2, v2, 0x3c800000, v211
	v_rsq_f32_e32 v2, v2
	s_nop 0
	v_pk_mul_f32 v[112:113], v[112:113], v[2:3] op_sel_hi:[1,0]
	v_pk_mul_f32 v[114:115], v[114:115], v[2:3] op_sel_hi:[1,0]
	v_pk_mul_f32 v[108:109], v[108:109], v[2:3] op_sel_hi:[1,0]
	v_pk_mul_f32 v[110:111], v[110:111], v[2:3] op_sel_hi:[1,0]
	v_pk_mul_f32 v[80:81], v[80:81], v[2:3] op_sel_hi:[1,0]
	v_pk_mul_f32 v[82:83], v[82:83], v[2:3] op_sel_hi:[1,0]
	v_pk_mul_f32 v[76:77], v[76:77], v[2:3] op_sel_hi:[1,0]
	v_pk_mul_f32 v[78:79], v[78:79], v[2:3] op_sel_hi:[1,0]
	v_pk_mul_f32 v[112:113], v[112:113], v[176:177]
	v_pk_mul_f32 v[114:115], v[114:115], v[178:179]
	v_pk_mul_f32 v[108:109], v[108:109], v[206:207]
	v_pk_mul_f32 v[110:111], v[110:111], v[208:209]
	v_pk_mul_f32 v[80:81], v[80:81], v[224:225]
	v_pk_mul_f32 v[82:83], v[82:83], v[226:227]
	v_pk_mul_f32 v[76:77], v[76:77], v[228:229]
	v_pk_mul_f32 v[78:79], v[78:79], v[230:231]
	v_cvt_pk_f16_f32 v152, v112, v113
	v_cvt_pk_f16_f32 v153, v114, v115
	v_cvt_pk_f16_f32 v154, v108, v109
	v_cvt_pk_f16_f32 v155, v110, v111
	global_store_dwordx4 v133, v[152:155], s[6:7] nt
	v_cvt_pk_f16_f32 v156, v80, v81
	v_cvt_pk_f16_f32 v157, v82, v83
	v_cvt_pk_f16_f32 v158, v76, v77
	v_cvt_pk_f16_f32 v159, v78, v79
	global_store_dwordx4 v133, v[156:159], s[6:7] offset:64 nt
	s_add_u32 s6, s4, 0x30000
	s_addc_u32 s7, s5, 0
	v_pk_mul_f32 v[104:105], v[104:105], v[140:141] op_sel_hi:[1,0]
	v_pk_mul_f32 v[106:107], v[106:107], v[140:141] op_sel_hi:[1,0]
	v_pk_mul_f32 v[100:101], v[100:101], v[140:141] op_sel_hi:[1,0]
	v_pk_mul_f32 v[102:103], v[102:103], v[140:141] op_sel_hi:[1,0]
	v_pk_mul_f32 v[72:73], v[72:73], v[140:141] op_sel_hi:[1,0]
	v_pk_mul_f32 v[74:75], v[74:75], v[140:141] op_sel_hi:[1,0]
	v_pk_mul_f32 v[68:69], v[68:69], v[140:141] op_sel_hi:[1,0]
	v_pk_mul_f32 v[70:71], v[70:71], v[140:141] op_sel_hi:[1,0]
	v_mul_f32_e32 v2, v104, v104
	v_mul_f32_e32 v150, v105, v105
	v_fmac_f32_e32 v2, v106, v106
	v_fmac_f32_e32 v150, v107, v107
	v_fmac_f32_e32 v2, v100, v100
	v_fmac_f32_e32 v150, v101, v101
	v_fmac_f32_e32 v2, v102, v102
	v_fmac_f32_e32 v150, v103, v103
	v_fmac_f32_e32 v2, v72, v72
	v_fmac_f32_e32 v150, v73, v73
	v_fmac_f32_e32 v2, v74, v74
	v_fmac_f32_e32 v150, v75, v75
	v_fmac_f32_e32 v2, v68, v68
	v_fmac_f32_e32 v150, v69, v69
	v_fmac_f32_e32 v2, v70, v70
	v_fmac_f32_e32 v150, v71, v71
	v_add_f32_e32 v2, v2, v150
	v_mov_b32_e32 v150, v2
	s_nop 1
	v_permlane16_swap_b32_e32 v2, v150
	v_add_f32_e32 v2, v2, v150
	v_mov_b32_e32 v150, v2
	s_nop 1
	v_permlane32_swap_b32_e32 v2, v150
	v_add_f32_e32 v2, v2, v150
	v_fmamk_f32 v2, v2, 0x3c800000, v211
	v_rsq_f32_e32 v2, v2
	s_nop 0
	v_pk_mul_f32 v[104:105], v[104:105], v[2:3] op_sel_hi:[1,0]
	v_pk_mul_f32 v[106:107], v[106:107], v[2:3] op_sel_hi:[1,0]
	v_pk_mul_f32 v[100:101], v[100:101], v[2:3] op_sel_hi:[1,0]
	v_pk_mul_f32 v[102:103], v[102:103], v[2:3] op_sel_hi:[1,0]
	v_pk_mul_f32 v[72:73], v[72:73], v[2:3] op_sel_hi:[1,0]
	v_pk_mul_f32 v[74:75], v[74:75], v[2:3] op_sel_hi:[1,0]
	v_pk_mul_f32 v[68:69], v[68:69], v[2:3] op_sel_hi:[1,0]
	v_pk_mul_f32 v[70:71], v[70:71], v[2:3] op_sel_hi:[1,0]
	v_pk_mul_f32 v[104:105], v[104:105], v[176:177]
	v_pk_mul_f32 v[106:107], v[106:107], v[178:179]
	v_pk_mul_f32 v[100:101], v[100:101], v[206:207]
	v_pk_mul_f32 v[102:103], v[102:103], v[208:209]
	v_pk_mul_f32 v[72:73], v[72:73], v[224:225]
	v_pk_mul_f32 v[74:75], v[74:75], v[226:227]
	v_pk_mul_f32 v[68:69], v[68:69], v[228:229]
	v_pk_mul_f32 v[70:71], v[70:71], v[230:231]
	v_cvt_pk_f16_f32 v160, v104, v105
	v_cvt_pk_f16_f32 v161, v106, v107
	v_cvt_pk_f16_f32 v162, v100, v101
	v_cvt_pk_f16_f32 v163, v102, v103
	global_store_dwordx4 v133, v[160:163], s[6:7] nt
	v_cvt_pk_f16_f32 v164, v72, v73
	v_cvt_pk_f16_f32 v165, v74, v75
	v_cvt_pk_f16_f32 v166, v68, v69
	v_cvt_pk_f16_f32 v167, v70, v71
	global_store_dwordx4 v133, v[164:167], s[6:7] offset:64 nt
; #define GAS __attribute__((address_space(1)))
; __host__ __device__ __forceinline__ size_t bl512(size_t row, int col) { return ((row >> 5) * 64 + (size_t)(col >> 3)) * 256 + (row & 31) * 8 + (col & 7); }
; __device__ __forceinline__ float silu_f(float v) { return v * __builtin_amdgcn_rcpf(1.0f + __builtin_amdgcn_exp2f(-v * LOG2E)); }
;     __device__ __forceinline__ void operator()(const f32x4 (&acc)[2][2][4][2], const Unit& u, int wr, int wc, int fr, int fq) const {
;     ...
;                 if (sec == 4 || sec == 5) {
;                     float ss = 0.f;
; #pragma unroll
;                     for (int bj = 0; bj < 2; ++bj)
; #pragma unroll
;                         for (int n = 0; n < 2; ++n) { const f32x4 x = v[bj][n]; ss += (x[0] * x[0] + x[1] * x[1]) + (x[2] * x[2] + x[3] * x[3]); }
;                     ss = row4_sum(ss);
;                     float rn = __builtin_amdgcn_rsqf(ss * (1.0f / 64.0f) + RMS_EPS);
;                     if (sec == 4) rn *= QS;
; #pragma unroll
;                     for (int bj = 0; bj < 2; ++bj)
; #pragma unroll
;                         for (int n = 0; n < 2; ++n) v[bj][n] = v[bj][n] * rn * gain[bj][n];
;                 } else if (sec == 0) {
; #pragma unroll
;                     for (int bj = 0; bj < 2; ++bj)
; #pragma unroll
;                         for (int n = 0; n < 2; ++n) v[bj][n] = v[bj][n] * QS;
;                 } else if (sec == 3 || sec == 7) {
; #pragma unroll
;                     for (int bj = 0; bj < 2; ++bj)
; #pragma unroll
;                         for (int n = 0; n < 2; ++n)
; #pragma unroll
;                             for (int e = 0; e < 4; ++e) v[bj][n][e] = silu_f(v[bj][n][e]);
;                 }
;                 GAS f16* rowp = isqg ? QG + (size_t)dsec * QG_SEC + bl512((size_t)row, cs) : KV + (size_t)row * KVW + dsec * 512 + cs;
; #pragma unroll
;                 for (int bj = 0; bj < 2; ++bj) {
;                     u32x4 w; w.x = pkh(v[bj][0][0], v[bj][0][1]); w.y = pkh(v[bj][0][2], v[bj][0][3]); w.z = pkh(v[bj][1][0], v[bj][1][1]); w.w = pkh(v[bj][1][2], v[bj][1][3]);
;                     *(GAS u32x4*)(rowp + bjstep * bj) = w;
;                 }
	s_add_u32 s6, s4, 0x80000
	s_addc_u32 s7, s5, 0
	v_pk_mul_f32 v[64:65], v[64:65], v[142:143] op_sel_hi:[1,0]
	v_pk_mul_f32 v[66:67], v[66:67], v[142:143] op_sel_hi:[1,0]
	v_pk_mul_f32 v[60:61], v[60:61], v[142:143] op_sel_hi:[1,0]
	v_pk_mul_f32 v[62:63], v[62:63], v[142:143] op_sel_hi:[1,0]
	v_pk_mul_f32 v[32:33], v[32:33], v[142:143] op_sel_hi:[1,0]
	v_pk_mul_f32 v[34:35], v[34:35], v[142:143] op_sel_hi:[1,0]
	v_pk_mul_f32 v[28:29], v[28:29], v[142:143] op_sel_hi:[1,0]
	v_pk_mul_f32 v[30:31], v[30:31], v[142:143] op_sel_hi:[1,0]
	v_mul_f32_e32 v2, v64, v64
	v_mul_f32_e32 v150, v65, v65
	v_fmac_f32_e32 v2, v66, v66
	v_fmac_f32_e32 v150, v67, v67
	v_fmac_f32_e32 v2, v60, v60
	v_fmac_f32_e32 v150, v61, v61
	v_fmac_f32_e32 v2, v62, v62
	v_fmac_f32_e32 v150, v63, v63
	v_fmac_f32_e32 v2, v32, v32
	v_fmac_f32_e32 v150, v33, v33
	v_fmac_f32_e32 v2, v34, v34
	v_fmac_f32_e32 v150, v35, v35
	v_fmac_f32_e32 v2, v28, v28
	v_fmac_f32_e32 v150, v29, v29
	v_fmac_f32_e32 v2, v30, v30
	v_fmac_f32_e32 v150, v31, v31
	v_add_f32_e32 v2, v2, v150
	v_mov_b32_e32 v150, v2
	s_nop 1
	v_permlane16_swap_b32_e32 v2, v150
	v_add_f32_e32 v2, v2, v150
	v_mov_b32_e32 v150, v2
	s_nop 1
	v_permlane32_swap_b32_e32 v2, v150
	v_add_f32_e32 v2, v2, v150
	v_fmamk_f32 v2, v2, 0x3c800000, v211
	v_rsq_f32_e32 v2, v2
	s_nop 0
	v_pk_mul_f32 v[64:65], v[64:65], v[2:3] op_sel_hi:[1,0]
	v_pk_mul_f32 v[66:67], v[66:67], v[2:3] op_sel_hi:[1,0]
	v_pk_mul_f32 v[60:61], v[60:61], v[2:3] op_sel_hi:[1,0]
	v_pk_mul_f32 v[62:63], v[62:63], v[2:3] op_sel_hi:[1,0]
	v_pk_mul_f32 v[32:33], v[32:33], v[2:3] op_sel_hi:[1,0]
	v_pk_mul_f32 v[34:35], v[34:35], v[2:3] op_sel_hi:[1,0]
	v_pk_mul_f32 v[28:29], v[28:29], v[2:3] op_sel_hi:[1,0]
	v_pk_mul_f32 v[30:31], v[30:31], v[2:3] op_sel_hi:[1,0]
	v_pk_mul_f32 v[64:65], v[64:65], v[176:177]
	v_pk_mul_f32 v[66:67], v[66:67], v[178:179]
	v_pk_mul_f32 v[60:61], v[60:61], v[206:207]
	v_pk_mul_f32 v[62:63], v[62:63], v[208:209]
	v_pk_mul_f32 v[32:33], v[32:33], v[224:225]
	v_pk_mul_f32 v[34:35], v[34:35], v[226:227]
	v_pk_mul_f32 v[28:29], v[28:29], v[228:229]
	v_pk_mul_f32 v[30:31], v[30:31], v[230:231]
	v_cvt_pk_f16_f32 v152, v64, v65
	v_cvt_pk_f16_f32 v153, v66, v67
	v_cvt_pk_f16_f32 v154, v60, v61
	v_cvt_pk_f16_f32 v155, v62, v63
	global_store_dwordx4 v133, v[152:155], s[6:7] nt
	v_cvt_pk_f16_f32 v156, v32, v33
	v_cvt_pk_f16_f32 v157, v34, v35
	v_cvt_pk_f16_f32 v158, v28, v29
	v_cvt_pk_f16_f32 v159, v30, v31
	global_store_dwordx4 v133, v[156:159], s[6:7] offset:64 nt
	s_add_u32 s6, s4, 0x90000
	s_addc_u32 s7, s5, 0
	v_pk_mul_f32 v[56:57], v[56:57], v[144:145] op_sel_hi:[1,0]
	v_pk_mul_f32 v[58:59], v[58:59], v[144:145] op_sel_hi:[1,0]
	v_pk_mul_f32 v[52:53], v[52:53], v[144:145] op_sel_hi:[1,0]
	v_pk_mul_f32 v[54:55], v[54:55], v[144:145] op_sel_hi:[1,0]
	v_pk_mul_f32 v[24:25], v[24:25], v[144:145] op_sel_hi:[1,0]
	v_pk_mul_f32 v[26:27], v[26:27], v[144:145] op_sel_hi:[1,0]
	v_pk_mul_f32 v[20:21], v[20:21], v[144:145] op_sel_hi:[1,0]
	v_pk_mul_f32 v[22:23], v[22:23], v[144:145] op_sel_hi:[1,0]
	v_mul_f32_e32 v2, v56, v56
	v_mul_f32_e32 v150, v57, v57
	v_fmac_f32_e32 v2, v58, v58
	v_fmac_f32_e32 v150, v59, v59
	v_fmac_f32_e32 v2, v52, v52
	v_fmac_f32_e32 v150, v53, v53
	v_fmac_f32_e32 v2, v54, v54
	v_fmac_f32_e32 v150, v55, v55
	v_fmac_f32_e32 v2, v24, v24
	v_fmac_f32_e32 v150, v25, v25
	v_fmac_f32_e32 v2, v26, v26
	v_fmac_f32_e32 v150, v27, v27
	v_fmac_f32_e32 v2, v20, v20
	v_fmac_f32_e32 v150, v21, v21
	v_fmac_f32_e32 v2, v22, v22
	v_fmac_f32_e32 v150, v23, v23
	v_add_f32_e32 v2, v2, v150
	v_mov_b32_e32 v150, v2
	s_nop 1
	v_permlane16_swap_b32_e32 v2, v150
	v_add_f32_e32 v2, v2, v150
	v_mov_b32_e32 v150, v2
	s_nop 1
	v_permlane32_swap_b32_e32 v2, v150
	v_add_f32_e32 v2, v2, v150
	v_fmamk_f32 v2, v2, 0x3c800000, v211
	v_rsq_f32_e32 v2, v2
	s_nop 0
	v_pk_mul_f32 v[56:57], v[56:57], v[2:3] op_sel_hi:[1,0]
	v_pk_mul_f32 v[58:59], v[58:59], v[2:3] op_sel_hi:[1,0]
	v_pk_mul_f32 v[52:53], v[52:53], v[2:3] op_sel_hi:[1,0]
	v_pk_mul_f32 v[54:55], v[54:55], v[2:3] op_sel_hi:[1,0]
	v_pk_mul_f32 v[24:25], v[24:25], v[2:3] op_sel_hi:[1,0]
	v_pk_mul_f32 v[26:27], v[26:27], v[2:3] op_sel_hi:[1,0]
	v_pk_mul_f32 v[20:21], v[20:21], v[2:3] op_sel_hi:[1,0]
	v_pk_mul_f32 v[22:23], v[22:23], v[2:3] op_sel_hi:[1,0]
	v_pk_mul_f32 v[56:57], v[56:57], v[176:177]
	v_pk_mul_f32 v[58:59], v[58:59], v[178:179]
	v_pk_mul_f32 v[52:53], v[52:53], v[206:207]
	v_pk_mul_f32 v[54:55], v[54:55], v[208:209]
	v_pk_mul_f32 v[24:25], v[24:25], v[224:225]
	v_pk_mul_f32 v[26:27], v[26:27], v[226:227]
	v_pk_mul_f32 v[20:21], v[20:21], v[228:229]
	v_pk_mul_f32 v[22:23], v[22:23], v[230:231]
	v_cvt_pk_f16_f32 v160, v56, v57
	v_cvt_pk_f16_f32 v161, v58, v59
	v_cvt_pk_f16_f32 v162, v52, v53
	v_cvt_pk_f16_f32 v163, v54, v55
	global_store_dwordx4 v133, v[160:163], s[6:7] nt
	v_cvt_pk_f16_f32 v164, v24, v25
	v_cvt_pk_f16_f32 v165, v26, v27
	v_cvt_pk_f16_f32 v166, v20, v21
	v_cvt_pk_f16_f32 v167, v22, v23
	global_store_dwordx4 v133, v[164:167], s[6:7] offset:64 nt
; #define GAS __attribute__((address_space(1)))
; __host__ __device__ __forceinline__ size_t bl512(size_t row, int col) { return ((row >> 5) * 64 + (size_t)(col >> 3)) * 256 + (row & 31) * 8 + (col & 7); }
; __device__ __forceinline__ float silu_f(float v) { return v * __builtin_amdgcn_rcpf(1.0f + __builtin_amdgcn_exp2f(-v * LOG2E)); }
;     __device__ __forceinline__ void operator()(const f32x4 (&acc)[2][2][4][2], const Unit& u, int wr, int wc, int fr, int fq) const {
;     ...
;                 if (sec == 4 || sec == 5) {
;                     float ss = 0.f;
; #pragma unroll
;                     for (int bj = 0; bj < 2; ++bj)
; #pragma unroll
;                         for (int n = 0; n < 2; ++n) { const f32x4 x = v[bj][n]; ss += (x[0] * x[0] + x[1] * x[1]) + (x[2] * x[2] + x[3] * x[3]); }
;                     ss = row4_sum(ss);
;                     float rn = __builtin_amdgcn_rsqf(ss * (1.0f / 64.0f) + RMS_EPS);
;                     if (sec == 4) rn *= QS;
; #pragma unroll
;                     for (int bj = 0; bj < 2; ++bj)
; #pragma unroll
;                         for (int n = 0; n < 2; ++n) v[bj][n] = v[bj][n] * rn * gain[bj][n];
;                 } else if (sec == 0) {
; #pragma unroll
;                     for (int bj = 0; bj < 2; ++bj)
; #pragma unroll
;                         for (int n = 0; n < 2; ++n) v[bj][n] = v[bj][n] * QS;
;                 } else if (sec == 3 || sec == 7) {
; #pragma unroll
;                     for (int bj = 0; bj < 2; ++bj)
; #pragma unroll
;                         for (int n = 0; n < 2; ++n)
; #pragma unroll
;                             for (int e = 0; e < 4; ++e) v[bj][n][e] = silu_f(v[bj][n][e]);
;                 }
;                 GAS f16* rowp = isqg ? QG + (size_t)dsec * QG_SEC + bl512((size_t)row, cs) : KV + (size_t)row * KVW + dsec * 512 + cs;
; #pragma unroll
;                 for (int bj = 0; bj < 2; ++bj) {
;                     u32x4 w; w.x = pkh(v[bj][0][0], v[bj][0][1]); w.y = pkh(v[bj][0][2], v[bj][0][3]); w.z = pkh(v[bj][1][0], v[bj][1][1]); w.w = pkh(v[bj][1][2], v[bj][1][3]);
;                     *(GAS u32x4*)(rowp + bjstep * bj) = w;
;                 }
	s_add_u32 s6, s4, 0xa0000
	s_addc_u32 s7, s5, 0
	v_pk_mul_f32 v[48:49], v[48:49], v[146:147] op_sel_hi:[1,0]
	v_pk_mul_f32 v[50:51], v[50:51], v[146:147] op_sel_hi:[1,0]
	v_pk_mul_f32 v[44:45], v[44:45], v[146:147] op_sel_hi:[1,0]
	v_pk_mul_f32 v[46:47], v[46:47], v[146:147] op_sel_hi:[1,0]
	v_pk_mul_f32 v[16:17], v[16:17], v[146:147] op_sel_hi:[1,0]
	v_pk_mul_f32 v[18:19], v[18:19], v[146:147] op_sel_hi:[1,0]
	v_pk_mul_f32 v[12:13], v[12:13], v[146:147] op_sel_hi:[1,0]
	v_pk_mul_f32 v[14:15], v[14:15], v[146:147] op_sel_hi:[1,0]
	v_mul_f32_e32 v2, v48, v48
	v_mul_f32_e32 v150, v49, v49
	v_fmac_f32_e32 v2, v50, v50
	v_fmac_f32_e32 v150, v51, v51
	v_fmac_f32_e32 v2, v44, v44
	v_fmac_f32_e32 v150, v45, v45
	v_fmac_f32_e32 v2, v46, v46
	v_fmac_f32_e32 v150, v47, v47
	v_fmac_f32_e32 v2, v16, v16
	v_fmac_f32_e32 v150, v17, v17
	v_fmac_f32_e32 v2, v18, v18
	v_fmac_f32_e32 v150, v19, v19
	v_fmac_f32_e32 v2, v12, v12
	v_fmac_f32_e32 v150, v13, v13
	v_fmac_f32_e32 v2, v14, v14
	v_fmac_f32_e32 v150, v15, v15
	v_add_f32_e32 v2, v2, v150
	v_mov_b32_e32 v150, v2
	s_nop 1
	v_permlane16_swap_b32_e32 v2, v150
	v_add_f32_e32 v2, v2, v150
	v_mov_b32_e32 v150, v2
	s_nop 1
	v_permlane32_swap_b32_e32 v2, v150
	v_add_f32_e32 v2, v2, v150
	v_fmamk_f32 v2, v2, 0x3c800000, v211
	v_rsq_f32_e32 v2, v2
	s_nop 0
	v_pk_mul_f32 v[48:49], v[48:49], v[2:3] op_sel_hi:[1,0]
	v_pk_mul_f32 v[50:51], v[50:51], v[2:3] op_sel_hi:[1,0]
	v_pk_mul_f32 v[44:45], v[44:45], v[2:3] op_sel_hi:[1,0]
	v_pk_mul_f32 v[46:47], v[46:47], v[2:3] op_sel_hi:[1,0]
	v_pk_mul_f32 v[16:17], v[16:17], v[2:3] op_sel_hi:[1,0]
	v_pk_mul_f32 v[18:19], v[18:19], v[2:3] op_sel_hi:[1,0]
	v_pk_mul_f32 v[12:13], v[12:13], v[2:3] op_sel_hi:[1,0]
	v_pk_mul_f32 v[14:15], v[14:15], v[2:3] op_sel_hi:[1,0]
	v_pk_mul_f32 v[48:49], v[48:49], v[176:177]
	v_pk_mul_f32 v[50:51], v[50:51], v[178:179]
	v_pk_mul_f32 v[44:45], v[44:45], v[206:207]
	v_pk_mul_f32 v[46:47], v[46:47], v[208:209]
	v_pk_mul_f32 v[16:17], v[16:17], v[224:225]
	v_pk_mul_f32 v[18:19], v[18:19], v[226:227]
	v_pk_mul_f32 v[12:13], v[12:13], v[228:229]
	v_pk_mul_f32 v[14:15], v[14:15], v[230:231]
	v_cvt_pk_f16_f32 v152, v48, v49
	v_cvt_pk_f16_f32 v153, v50, v51
	v_cvt_pk_f16_f32 v154, v44, v45
	v_cvt_pk_f16_f32 v155, v46, v47
	global_store_dwordx4 v133, v[152:155], s[6:7] nt
	v_cvt_pk_f16_f32 v156, v16, v17
	v_cvt_pk_f16_f32 v157, v18, v19
	v_cvt_pk_f16_f32 v158, v12, v13
	v_cvt_pk_f16_f32 v159, v14, v15
	global_store_dwordx4 v133, v[156:159], s[6:7] offset:64 nt
	s_add_u32 s6, s4, 0xb0000
	s_addc_u32 s7, s5, 0
	v_pk_mul_f32 v[40:41], v[40:41], v[148:149] op_sel_hi:[1,0]
	v_pk_mul_f32 v[42:43], v[42:43], v[148:149] op_sel_hi:[1,0]
	v_pk_mul_f32 v[36:37], v[36:37], v[148:149] op_sel_hi:[1,0]
	v_pk_mul_f32 v[38:39], v[38:39], v[148:149] op_sel_hi:[1,0]
	v_pk_mul_f32 v[8:9], v[8:9], v[148:149] op_sel_hi:[1,0]
	v_pk_mul_f32 v[10:11], v[10:11], v[148:149] op_sel_hi:[1,0]
	v_pk_mul_f32 v[4:5], v[4:5], v[148:149] op_sel_hi:[1,0]
	v_pk_mul_f32 v[6:7], v[6:7], v[148:149] op_sel_hi:[1,0]
	v_mul_f32_e32 v2, v40, v40
	v_mul_f32_e32 v150, v41, v41
	v_fmac_f32_e32 v2, v42, v42
	v_fmac_f32_e32 v150, v43, v43
	v_fmac_f32_e32 v2, v36, v36
	v_fmac_f32_e32 v150, v37, v37
	v_fmac_f32_e32 v2, v38, v38
	v_fmac_f32_e32 v150, v39, v39
	v_fmac_f32_e32 v2, v8, v8
	v_fmac_f32_e32 v150, v9, v9
	v_fmac_f32_e32 v2, v10, v10
	v_fmac_f32_e32 v150, v11, v11
	v_fmac_f32_e32 v2, v4, v4
	v_fmac_f32_e32 v150, v5, v5
	v_fmac_f32_e32 v2, v6, v6
	v_fmac_f32_e32 v150, v7, v7
	v_add_f32_e32 v2, v2, v150
	v_mov_b32_e32 v150, v2
	s_nop 1
	v_permlane16_swap_b32_e32 v2, v150
	v_add_f32_e32 v2, v2, v150
	v_mov_b32_e32 v150, v2
	s_nop 1
	v_permlane32_swap_b32_e32 v2, v150
	v_add_f32_e32 v2, v2, v150
	v_fmamk_f32 v2, v2, 0x3c800000, v211
	v_rsq_f32_e32 v2, v2
	s_nop 0
	v_pk_mul_f32 v[40:41], v[40:41], v[2:3] op_sel_hi:[1,0]
	v_pk_mul_f32 v[42:43], v[42:43], v[2:3] op_sel_hi:[1,0]
	v_pk_mul_f32 v[36:37], v[36:37], v[2:3] op_sel_hi:[1,0]
	v_pk_mul_f32 v[38:39], v[38:39], v[2:3] op_sel_hi:[1,0]
	v_pk_mul_f32 v[8:9], v[8:9], v[2:3] op_sel_hi:[1,0]
	v_pk_mul_f32 v[10:11], v[10:11], v[2:3] op_sel_hi:[1,0]
	v_pk_mul_f32 v[4:5], v[4:5], v[2:3] op_sel_hi:[1,0]
	v_pk_mul_f32 v[6:7], v[6:7], v[2:3] op_sel_hi:[1,0]
	v_pk_mul_f32 v[40:41], v[40:41], v[176:177]
	v_pk_mul_f32 v[42:43], v[42:43], v[178:179]
	v_pk_mul_f32 v[36:37], v[36:37], v[206:207]
	v_pk_mul_f32 v[38:39], v[38:39], v[208:209]
	v_pk_mul_f32 v[8:9], v[8:9], v[224:225]
	v_pk_mul_f32 v[10:11], v[10:11], v[226:227]
	v_pk_mul_f32 v[4:5], v[4:5], v[228:229]
	v_pk_mul_f32 v[6:7], v[6:7], v[230:231]
	v_cvt_pk_f16_f32 v160, v40, v41
	v_cvt_pk_f16_f32 v161, v42, v43
	v_cvt_pk_f16_f32 v162, v36, v37
	v_cvt_pk_f16_f32 v163, v38, v39
	global_store_dwordx4 v133, v[160:163], s[6:7] nt
	v_cvt_pk_f16_f32 v164, v8, v9
	v_cvt_pk_f16_f32 v165, v10, v11
	v_cvt_pk_f16_f32 v166, v4, v5
	v_cvt_pk_f16_f32 v167, v6, v7
	global_store_dwordx4 v133, v[164:167], s[6:7] offset:64 nt
	s_branch .Lepi_done_g1
